# residual GEMM epilogues rewritten by hand: 16-byte loads/stores via v_permlane16_swap pairs, 8 base loads in flight
# speedup vs baseline: 1.0475x; 1.0135x over previous
.LBB0_1883:
	s_lshl_b32 s4, s48, 8
	v_mov_b32_e32 v152, v140
	v_mov_b32_e32 v153, v141
	s_or_b32 s4, s4, s66
	s_nop 0
	v_lshl_add_u32 v136, v152, 2, s4
	s_lshl_b32 s4, s22, 8
	s_add_i32 s4, s4, s65
	v_add_u32_e32 v138, s4, v153
	v_ashrrev_i32_e32 v139, 31, v138
	v_lshlrev_b64 v[144:145], 11, v[138:139]
	v_ashrrev_i32_e32 v137, 31, v136
	v_lshl_add_u64 v[144:145], s[8:9], 0, v[144:145]
	v_lshl_add_u64 v[144:145], v[136:137], 1, v[144:145]
	v_and_b32_e32 v251, 1, v152
	v_lshlrev_b32_e32 v250, 11, v138
	v_mul_u32_u24_e32 v251, 24, v251
	v_lshl_add_u32 v250, v136, 1, v250
	v_add_u32_e32 v250, v250, v251
	global_load_dwordx4 v[216:219], v250, s[8:9]
	global_load_dwordx4 v[220:223], v250, s[8:9] offset:256
	v_add_u32_e32 v251, 0x8000, v250
	global_load_dwordx4 v[224:227], v251, s[8:9]
	global_load_dwordx4 v[228:231], v251, s[8:9] offset:256
	v_add_u32_e32 v251, 0x10000, v250
	global_load_dwordx4 v[232:235], v251, s[8:9]
	global_load_dwordx4 v[236:239], v251, s[8:9] offset:256
	v_add_u32_e32 v251, 0x18000, v250
	global_load_dwordx4 v[240:243], v251, s[8:9]
	global_load_dwordx4 v[244:247], v251, s[8:9] offset:256
	s_lshl_b32 s4, s48, 2
	v_cmp_eq_u32_e32 vcc, 0, v152
	s_ashr_i32 s5, s4, 31
	v_lshlrev_b64 v[148:149], 6, v[138:139]
	v_lshl_add_u64 v[148:149], s[10:11], 0, v[148:149]
	v_lshl_add_u64 v[148:149], s[4:5], 2, v[148:149]
	s_lshl_b32 s22, s64, 2
	v_lshl_add_u64 v[148:149], v[148:149], 0, s[22:23]
	s_movk_i32 s22, 0x2000
	v_lshl_add_u64 v[150:151], v[148:149], 0, s[22:23]
	s_waitcnt vmcnt(7)
	v_permlane16_swap_b32_e32 v216, v218
	v_permlane16_swap_b32_e32 v217, v219
	v_lshlrev_b32_e32 v144, 16, v216
	v_and_b32_e32 v145, 0xffff0000, v216
	v_lshlrev_b32_e32 v146, 16, v217
	v_and_b32_e32 v147, 0xffff0000, v217
	v_pk_add_f32 v[126:127], v[126:127], v[144:145]
	v_pk_add_f32 v[128:129], v[128:129], v[146:147]
	v_lshlrev_b32_e32 v144, 16, v218
	v_and_b32_e32 v145, 0xffff0000, v218
	v_lshlrev_b32_e32 v146, 16, v219
	v_and_b32_e32 v147, 0xffff0000, v219
	v_pk_add_f32 v[122:123], v[122:123], v[144:145]
	v_pk_add_f32 v[124:125], v[124:125], v[146:147]
	v_mul_f32_e32 v248, v126, v126
	v_mul_f32_e32 v249, v122, v122
	v_fmac_f32_e32 v248, v127, v127
	v_fmac_f32_e32 v249, v123, v123
	v_fmac_f32_e32 v248, v128, v128
	v_fmac_f32_e32 v249, v124, v124
	v_fmac_f32_e32 v248, v129, v129
	v_fmac_f32_e32 v249, v125, v125
	v_add_f32_e32 v248, v248, v249
	v_mov_b32_e32 v252, v248
	v_cvt_pk_bf16_f32 v216, v126, v127
	v_cvt_pk_bf16_f32 v217, v128, v129
	v_cvt_pk_bf16_f32 v218, v122, v123
	v_cvt_pk_bf16_f32 v219, v124, v125
	s_nop 1
	v_permlane16_swap_b32_e32 v216, v218
	v_permlane16_swap_b32_e32 v217, v219
	global_store_dwordx4 v250, v[216:219], s[8:9]
	v_add_u32_e32 v251, 0x40000, v250
	s_nop 0
	global_load_dwordx4 v[216:219], v251, s[8:9]
	s_waitcnt vmcnt(8)
	v_permlane16_swap_b32_e32 v220, v222
	v_permlane16_swap_b32_e32 v221, v223
	v_lshlrev_b32_e32 v144, 16, v220
	v_and_b32_e32 v145, 0xffff0000, v220
	v_lshlrev_b32_e32 v146, 16, v221
	v_and_b32_e32 v147, 0xffff0000, v221
	v_pk_add_f32 v[118:119], v[118:119], v[144:145]
	v_pk_add_f32 v[120:121], v[120:121], v[146:147]
	v_lshlrev_b32_e32 v144, 16, v222
	v_and_b32_e32 v145, 0xffff0000, v222
	v_lshlrev_b32_e32 v146, 16, v223
	v_and_b32_e32 v147, 0xffff0000, v223
	v_pk_add_f32 v[114:115], v[114:115], v[144:145]
	v_pk_add_f32 v[116:117], v[116:117], v[146:147]
	v_mul_f32_e32 v248, v118, v118
	v_mul_f32_e32 v249, v114, v114
	v_fmac_f32_e32 v248, v119, v119
	v_fmac_f32_e32 v249, v115, v115
	v_fmac_f32_e32 v248, v120, v120
	v_fmac_f32_e32 v249, v116, v116
	v_fmac_f32_e32 v248, v121, v121
	v_fmac_f32_e32 v249, v117, v117
	v_add_f32_e32 v248, v248, v249
	v_add_f32_e32 v252, v252, v248
	v_cvt_pk_bf16_f32 v220, v118, v119
	v_cvt_pk_bf16_f32 v221, v120, v121
	v_cvt_pk_bf16_f32 v222, v114, v115
	v_cvt_pk_bf16_f32 v223, v116, v117
	s_nop 1
	v_permlane16_swap_b32_e32 v220, v222
	v_permlane16_swap_b32_e32 v221, v223
	global_store_dwordx4 v250, v[220:223], s[8:9] offset:256
	v_lshlrev_b32_e32 v118, 2, v153
	v_lshl_add_u32 v119, v152, 6, v118
	v_xor_b32_e32 v118, 64, v119
	v_xor_b32_e32 v116, 0x80, v119
	ds_bpermute_b32 v248, v118, v252
	s_waitcnt lgkmcnt(0)
	v_add_f32_e32 v252, v252, v248
	ds_bpermute_b32 v248, v116, v252
	s_nop 0
	global_load_dwordx4 v[220:223], v251, s[8:9] offset:256
	s_and_saveexec_b64 s[48:49], vcc
	s_cbranch_execz .Lepi5_g0
	s_waitcnt lgkmcnt(0)
	v_add_f32_e32 v252, v252, v248
	global_store_dword v[148:149], v252, off
.Lepi5_g0:
	s_or_b64 exec, exec, s[48:49]
	s_waitcnt lgkmcnt(0)
	s_waitcnt vmcnt(10)
	v_permlane16_swap_b32_e32 v224, v226
	v_permlane16_swap_b32_e32 v225, v227
	v_lshlrev_b32_e32 v144, 16, v224
	v_and_b32_e32 v145, 0xffff0000, v224
	v_lshlrev_b32_e32 v146, 16, v225
	v_and_b32_e32 v147, 0xffff0000, v225
	v_pk_add_f32 v[110:111], v[110:111], v[144:145]
	v_pk_add_f32 v[112:113], v[112:113], v[146:147]
	v_lshlrev_b32_e32 v144, 16, v226
	v_and_b32_e32 v145, 0xffff0000, v226
	v_lshlrev_b32_e32 v146, 16, v227
	v_and_b32_e32 v147, 0xffff0000, v227
	v_pk_add_f32 v[106:107], v[106:107], v[144:145]
	v_pk_add_f32 v[108:109], v[108:109], v[146:147]
	v_mul_f32_e32 v248, v110, v110
	v_mul_f32_e32 v249, v106, v106
	v_fmac_f32_e32 v248, v111, v111
	v_fmac_f32_e32 v249, v107, v107
	v_fmac_f32_e32 v248, v112, v112
	v_fmac_f32_e32 v249, v108, v108
	v_fmac_f32_e32 v248, v113, v113
	v_fmac_f32_e32 v249, v109, v109
	v_add_f32_e32 v248, v248, v249
	v_mov_b32_e32 v252, v248
	v_cvt_pk_bf16_f32 v224, v110, v111
	v_cvt_pk_bf16_f32 v225, v112, v113
	v_cvt_pk_bf16_f32 v226, v106, v107
	v_cvt_pk_bf16_f32 v227, v108, v109
	s_nop 1
	v_permlane16_swap_b32_e32 v224, v226
	v_permlane16_swap_b32_e32 v225, v227
	v_add_u32_e32 v253, 0x8000, v250
	global_store_dwordx4 v253, v[224:227], s[8:9]
	v_add_u32_e32 v251, 0x48000, v250
	s_nop 0
	global_load_dwordx4 v[224:227], v251, s[8:9]
	s_waitcnt vmcnt(11)
	v_permlane16_swap_b32_e32 v228, v230
	v_permlane16_swap_b32_e32 v229, v231
	v_lshlrev_b32_e32 v144, 16, v228
	v_and_b32_e32 v145, 0xffff0000, v228
	v_lshlrev_b32_e32 v146, 16, v229
	v_and_b32_e32 v147, 0xffff0000, v229
	v_pk_add_f32 v[102:103], v[102:103], v[144:145]
	v_pk_add_f32 v[104:105], v[104:105], v[146:147]
	v_lshlrev_b32_e32 v144, 16, v230
	v_and_b32_e32 v145, 0xffff0000, v230
	v_lshlrev_b32_e32 v146, 16, v231
	v_and_b32_e32 v147, 0xffff0000, v231
	v_pk_add_f32 v[98:99], v[98:99], v[144:145]
	v_pk_add_f32 v[100:101], v[100:101], v[146:147]
	v_mul_f32_e32 v248, v102, v102
	v_mul_f32_e32 v249, v98, v98
	v_fmac_f32_e32 v248, v103, v103
	v_fmac_f32_e32 v249, v99, v99
	v_fmac_f32_e32 v248, v104, v104
	v_fmac_f32_e32 v249, v100, v100
	v_fmac_f32_e32 v248, v105, v105
	v_fmac_f32_e32 v249, v101, v101
	v_add_f32_e32 v248, v248, v249
	v_add_f32_e32 v252, v252, v248
	v_cvt_pk_bf16_f32 v228, v102, v103
	v_cvt_pk_bf16_f32 v229, v104, v105
	v_cvt_pk_bf16_f32 v230, v98, v99
	v_cvt_pk_bf16_f32 v231, v100, v101
	s_nop 1
	v_permlane16_swap_b32_e32 v228, v230
	v_permlane16_swap_b32_e32 v229, v231
	global_store_dwordx4 v253, v[228:231], s[8:9] offset:256
	ds_bpermute_b32 v248, v118, v252
	s_waitcnt lgkmcnt(0)
	v_add_f32_e32 v252, v252, v248
	ds_bpermute_b32 v248, v116, v252
	s_nop 0
	global_load_dwordx4 v[228:231], v251, s[8:9] offset:256
	s_and_saveexec_b64 s[48:49], vcc
	s_cbranch_execz .Lepi5_g1
	s_waitcnt lgkmcnt(0)
	v_add_f32_e32 v252, v252, v248
	global_store_dword v[148:149], v252, off offset:1024
.Lepi5_g1:
	s_or_b64 exec, exec, s[48:49]
	s_waitcnt lgkmcnt(0)
	s_waitcnt vmcnt(13)
	v_permlane16_swap_b32_e32 v232, v234
	v_permlane16_swap_b32_e32 v233, v235
	v_lshlrev_b32_e32 v144, 16, v232
	v_and_b32_e32 v145, 0xffff0000, v232
	v_lshlrev_b32_e32 v146, 16, v233
	v_and_b32_e32 v147, 0xffff0000, v233
	v_pk_add_f32 v[94:95], v[94:95], v[144:145]
	v_pk_add_f32 v[96:97], v[96:97], v[146:147]
	v_lshlrev_b32_e32 v144, 16, v234
	v_and_b32_e32 v145, 0xffff0000, v234
	v_lshlrev_b32_e32 v146, 16, v235
	v_and_b32_e32 v147, 0xffff0000, v235
	v_pk_add_f32 v[90:91], v[90:91], v[144:145]
	v_pk_add_f32 v[92:93], v[92:93], v[146:147]
	v_mul_f32_e32 v248, v94, v94
	v_mul_f32_e32 v249, v90, v90
	v_fmac_f32_e32 v248, v95, v95
	v_fmac_f32_e32 v249, v91, v91
	v_fmac_f32_e32 v248, v96, v96
	v_fmac_f32_e32 v249, v92, v92
	v_fmac_f32_e32 v248, v97, v97
	v_fmac_f32_e32 v249, v93, v93
	v_add_f32_e32 v248, v248, v249
	v_mov_b32_e32 v252, v248
	v_cvt_pk_bf16_f32 v232, v94, v95
	v_cvt_pk_bf16_f32 v233, v96, v97
	v_cvt_pk_bf16_f32 v234, v90, v91
	v_cvt_pk_bf16_f32 v235, v92, v93
	s_nop 1
	v_permlane16_swap_b32_e32 v232, v234
	v_permlane16_swap_b32_e32 v233, v235
	v_add_u32_e32 v253, 0x10000, v250
	global_store_dwordx4 v253, v[232:235], s[8:9]
	v_add_u32_e32 v251, 0x50000, v250
	s_nop 0
	global_load_dwordx4 v[232:235], v251, s[8:9]
	s_waitcnt vmcnt(14)
	v_permlane16_swap_b32_e32 v236, v238
	v_permlane16_swap_b32_e32 v237, v239
	v_lshlrev_b32_e32 v144, 16, v236
	v_and_b32_e32 v145, 0xffff0000, v236
	v_lshlrev_b32_e32 v146, 16, v237
	v_and_b32_e32 v147, 0xffff0000, v237
	v_pk_add_f32 v[86:87], v[86:87], v[144:145]
	v_pk_add_f32 v[88:89], v[88:89], v[146:147]
	v_lshlrev_b32_e32 v144, 16, v238
	v_and_b32_e32 v145, 0xffff0000, v238
	v_lshlrev_b32_e32 v146, 16, v239
	v_and_b32_e32 v147, 0xffff0000, v239
	v_pk_add_f32 v[82:83], v[82:83], v[144:145]
	v_pk_add_f32 v[84:85], v[84:85], v[146:147]
	v_mul_f32_e32 v248, v86, v86
	v_mul_f32_e32 v249, v82, v82
	v_fmac_f32_e32 v248, v87, v87
	v_fmac_f32_e32 v249, v83, v83
	v_fmac_f32_e32 v248, v88, v88
	v_fmac_f32_e32 v249, v84, v84
	v_fmac_f32_e32 v248, v89, v89
	v_fmac_f32_e32 v249, v85, v85
	v_add_f32_e32 v248, v248, v249
	v_add_f32_e32 v252, v252, v248
	v_cvt_pk_bf16_f32 v236, v86, v87
	v_cvt_pk_bf16_f32 v237, v88, v89
	v_cvt_pk_bf16_f32 v238, v82, v83
	v_cvt_pk_bf16_f32 v239, v84, v85
	s_nop 1
	v_permlane16_swap_b32_e32 v236, v238
	v_permlane16_swap_b32_e32 v237, v239
	global_store_dwordx4 v253, v[236:239], s[8:9] offset:256
	ds_bpermute_b32 v248, v118, v252
	s_waitcnt lgkmcnt(0)
	v_add_f32_e32 v252, v252, v248
	ds_bpermute_b32 v248, v116, v252
	s_nop 0
	global_load_dwordx4 v[236:239], v251, s[8:9] offset:256
	s_and_saveexec_b64 s[48:49], vcc
	s_cbranch_execz .Lepi5_g2
	s_waitcnt lgkmcnt(0)
	v_add_f32_e32 v252, v252, v248
	global_store_dword v[148:149], v252, off offset:2048
.Lepi5_g2:
	s_or_b64 exec, exec, s[48:49]
	s_waitcnt lgkmcnt(0)
	s_waitcnt vmcnt(16)
	v_permlane16_swap_b32_e32 v240, v242
	v_permlane16_swap_b32_e32 v241, v243
	v_lshlrev_b32_e32 v144, 16, v240
	v_and_b32_e32 v145, 0xffff0000, v240
	v_lshlrev_b32_e32 v146, 16, v241
	v_and_b32_e32 v147, 0xffff0000, v241
	v_pk_add_f32 v[78:79], v[78:79], v[144:145]
	v_pk_add_f32 v[80:81], v[80:81], v[146:147]
	v_lshlrev_b32_e32 v144, 16, v242
	v_and_b32_e32 v145, 0xffff0000, v242
	v_lshlrev_b32_e32 v146, 16, v243
	v_and_b32_e32 v147, 0xffff0000, v243
	v_pk_add_f32 v[74:75], v[74:75], v[144:145]
	v_pk_add_f32 v[76:77], v[76:77], v[146:147]
	v_mul_f32_e32 v248, v78, v78
	v_mul_f32_e32 v249, v74, v74
	v_fmac_f32_e32 v248, v79, v79
	v_fmac_f32_e32 v249, v75, v75
	v_fmac_f32_e32 v248, v80, v80
	v_fmac_f32_e32 v249, v76, v76
	v_fmac_f32_e32 v248, v81, v81
	v_fmac_f32_e32 v249, v77, v77
	v_add_f32_e32 v248, v248, v249
	v_mov_b32_e32 v252, v248
	v_cvt_pk_bf16_f32 v240, v78, v79
	v_cvt_pk_bf16_f32 v241, v80, v81
	v_cvt_pk_bf16_f32 v242, v74, v75
	v_cvt_pk_bf16_f32 v243, v76, v77
	s_nop 1
	v_permlane16_swap_b32_e32 v240, v242
	v_permlane16_swap_b32_e32 v241, v243
	v_add_u32_e32 v253, 0x18000, v250
	global_store_dwordx4 v253, v[240:243], s[8:9]
	v_add_u32_e32 v251, 0x58000, v250
	s_nop 0
	global_load_dwordx4 v[240:243], v251, s[8:9]
	s_waitcnt vmcnt(17)
	v_permlane16_swap_b32_e32 v244, v246
	v_permlane16_swap_b32_e32 v245, v247
	v_lshlrev_b32_e32 v144, 16, v244
	v_and_b32_e32 v145, 0xffff0000, v244
	v_lshlrev_b32_e32 v146, 16, v245
	v_and_b32_e32 v147, 0xffff0000, v245
	v_pk_add_f32 v[70:71], v[70:71], v[144:145]
	v_pk_add_f32 v[72:73], v[72:73], v[146:147]
	v_lshlrev_b32_e32 v144, 16, v246
	v_and_b32_e32 v145, 0xffff0000, v246
	v_lshlrev_b32_e32 v146, 16, v247
	v_and_b32_e32 v147, 0xffff0000, v247
	v_pk_add_f32 v[66:67], v[66:67], v[144:145]
	v_pk_add_f32 v[68:69], v[68:69], v[146:147]
	v_mul_f32_e32 v248, v70, v70
	v_mul_f32_e32 v249, v66, v66
	v_fmac_f32_e32 v248, v71, v71
	v_fmac_f32_e32 v249, v67, v67
	v_fmac_f32_e32 v248, v72, v72
	v_fmac_f32_e32 v249, v68, v68
	v_fmac_f32_e32 v248, v73, v73
	v_fmac_f32_e32 v249, v69, v69
	v_add_f32_e32 v248, v248, v249
	v_add_f32_e32 v252, v252, v248
	v_cvt_pk_bf16_f32 v244, v70, v71
	v_cvt_pk_bf16_f32 v245, v72, v73
	v_cvt_pk_bf16_f32 v246, v66, v67
	v_cvt_pk_bf16_f32 v247, v68, v69
	s_nop 1
	v_permlane16_swap_b32_e32 v244, v246
	v_permlane16_swap_b32_e32 v245, v247
	global_store_dwordx4 v253, v[244:247], s[8:9] offset:256
	ds_bpermute_b32 v248, v118, v252
	s_waitcnt lgkmcnt(0)
	v_add_f32_e32 v252, v252, v248
	ds_bpermute_b32 v248, v116, v252
	s_nop 0
	global_load_dwordx4 v[244:247], v251, s[8:9] offset:256
	s_and_saveexec_b64 s[48:49], vcc
	s_cbranch_execz .Lepi5_g3
	s_waitcnt lgkmcnt(0)
	v_add_f32_e32 v252, v252, v248
	global_store_dword v[148:149], v252, off offset:3072
.Lepi5_g3:
	s_or_b64 exec, exec, s[48:49]
	s_waitcnt lgkmcnt(0)
	s_waitcnt vmcnt(18)
	v_permlane16_swap_b32_e32 v216, v218
	v_permlane16_swap_b32_e32 v217, v219
	v_lshlrev_b32_e32 v144, 16, v216
	v_and_b32_e32 v145, 0xffff0000, v216
	v_lshlrev_b32_e32 v146, 16, v217
	v_and_b32_e32 v147, 0xffff0000, v217
	v_pk_add_f32 v[62:63], v[62:63], v[144:145]
	v_pk_add_f32 v[64:65], v[64:65], v[146:147]
	v_lshlrev_b32_e32 v144, 16, v218
	v_and_b32_e32 v145, 0xffff0000, v218
	v_lshlrev_b32_e32 v146, 16, v219
	v_and_b32_e32 v147, 0xffff0000, v219
	v_pk_add_f32 v[58:59], v[58:59], v[144:145]
	v_pk_add_f32 v[60:61], v[60:61], v[146:147]
	v_mul_f32_e32 v248, v62, v62
	v_mul_f32_e32 v249, v58, v58
	v_fmac_f32_e32 v248, v63, v63
	v_fmac_f32_e32 v249, v59, v59
	v_fmac_f32_e32 v248, v64, v64
	v_fmac_f32_e32 v249, v60, v60
	v_fmac_f32_e32 v248, v65, v65
	v_fmac_f32_e32 v249, v61, v61
	v_add_f32_e32 v248, v248, v249
	v_mov_b32_e32 v252, v248
	v_cvt_pk_bf16_f32 v216, v62, v63
	v_cvt_pk_bf16_f32 v217, v64, v65
	v_cvt_pk_bf16_f32 v218, v58, v59
	v_cvt_pk_bf16_f32 v219, v60, v61
	s_nop 1
	v_permlane16_swap_b32_e32 v216, v218
	v_permlane16_swap_b32_e32 v217, v219
	v_add_u32_e32 v253, 0x40000, v250
	global_store_dwordx4 v253, v[216:219], s[8:9]
	s_waitcnt vmcnt(17)
	v_permlane16_swap_b32_e32 v220, v222
	v_permlane16_swap_b32_e32 v221, v223
	v_lshlrev_b32_e32 v144, 16, v220
	v_and_b32_e32 v145, 0xffff0000, v220
	v_lshlrev_b32_e32 v146, 16, v221
	v_and_b32_e32 v147, 0xffff0000, v221
	v_pk_add_f32 v[54:55], v[54:55], v[144:145]
	v_pk_add_f32 v[56:57], v[56:57], v[146:147]
	v_lshlrev_b32_e32 v144, 16, v222
	v_and_b32_e32 v145, 0xffff0000, v222
	v_lshlrev_b32_e32 v146, 16, v223
	v_and_b32_e32 v147, 0xffff0000, v223
	v_pk_add_f32 v[50:51], v[50:51], v[144:145]
	v_pk_add_f32 v[52:53], v[52:53], v[146:147]
	v_mul_f32_e32 v248, v54, v54
	v_mul_f32_e32 v249, v50, v50
	v_fmac_f32_e32 v248, v55, v55
	v_fmac_f32_e32 v249, v51, v51
	v_fmac_f32_e32 v248, v56, v56
	v_fmac_f32_e32 v249, v52, v52
	v_fmac_f32_e32 v248, v57, v57
	v_fmac_f32_e32 v249, v53, v53
	v_add_f32_e32 v248, v248, v249
	v_add_f32_e32 v252, v252, v248
	v_cvt_pk_bf16_f32 v220, v54, v55
	v_cvt_pk_bf16_f32 v221, v56, v57
	v_cvt_pk_bf16_f32 v222, v50, v51
	v_cvt_pk_bf16_f32 v223, v52, v53
	s_nop 1
	v_permlane16_swap_b32_e32 v220, v222
	v_permlane16_swap_b32_e32 v221, v223
	global_store_dwordx4 v253, v[220:223], s[8:9] offset:256
	ds_bpermute_b32 v248, v118, v252
	s_waitcnt lgkmcnt(0)
	v_add_f32_e32 v252, v252, v248
	ds_bpermute_b32 v248, v116, v252
	s_and_saveexec_b64 s[48:49], vcc
	s_cbranch_execz .Lepi5_g4
	s_waitcnt lgkmcnt(0)
	v_add_f32_e32 v252, v252, v248
	global_store_dword v[150:151], v252, off
.Lepi5_g4:
	s_or_b64 exec, exec, s[48:49]
	s_waitcnt lgkmcnt(0)
	s_waitcnt vmcnt(16)
	v_permlane16_swap_b32_e32 v224, v226
	v_permlane16_swap_b32_e32 v225, v227
	v_lshlrev_b32_e32 v144, 16, v224
	v_and_b32_e32 v145, 0xffff0000, v224
	v_lshlrev_b32_e32 v146, 16, v225
	v_and_b32_e32 v147, 0xffff0000, v225
	v_pk_add_f32 v[46:47], v[46:47], v[144:145]
	v_pk_add_f32 v[48:49], v[48:49], v[146:147]
	v_lshlrev_b32_e32 v144, 16, v226
	v_and_b32_e32 v145, 0xffff0000, v226
	v_lshlrev_b32_e32 v146, 16, v227
	v_and_b32_e32 v147, 0xffff0000, v227
	v_pk_add_f32 v[42:43], v[42:43], v[144:145]
	v_pk_add_f32 v[44:45], v[44:45], v[146:147]
	v_mul_f32_e32 v248, v46, v46
	v_mul_f32_e32 v249, v42, v42
	v_fmac_f32_e32 v248, v47, v47
	v_fmac_f32_e32 v249, v43, v43
	v_fmac_f32_e32 v248, v48, v48
	v_fmac_f32_e32 v249, v44, v44
	v_fmac_f32_e32 v248, v49, v49
	v_fmac_f32_e32 v249, v45, v45
	v_add_f32_e32 v248, v248, v249
	v_mov_b32_e32 v252, v248
	v_cvt_pk_bf16_f32 v224, v46, v47
	v_cvt_pk_bf16_f32 v225, v48, v49
	v_cvt_pk_bf16_f32 v226, v42, v43
	v_cvt_pk_bf16_f32 v227, v44, v45
	s_nop 1
	v_permlane16_swap_b32_e32 v224, v226
	v_permlane16_swap_b32_e32 v225, v227
	v_add_u32_e32 v253, 0x48000, v250
	global_store_dwordx4 v253, v[224:227], s[8:9]
	s_waitcnt vmcnt(15)
	v_permlane16_swap_b32_e32 v228, v230
	v_permlane16_swap_b32_e32 v229, v231
	v_lshlrev_b32_e32 v144, 16, v228
	v_and_b32_e32 v145, 0xffff0000, v228
	v_lshlrev_b32_e32 v146, 16, v229
	v_and_b32_e32 v147, 0xffff0000, v229
	v_pk_add_f32 v[38:39], v[38:39], v[144:145]
	v_pk_add_f32 v[40:41], v[40:41], v[146:147]
	v_lshlrev_b32_e32 v144, 16, v230
	v_and_b32_e32 v145, 0xffff0000, v230
	v_lshlrev_b32_e32 v146, 16, v231
	v_and_b32_e32 v147, 0xffff0000, v231
	v_pk_add_f32 v[34:35], v[34:35], v[144:145]
	v_pk_add_f32 v[36:37], v[36:37], v[146:147]
	v_mul_f32_e32 v248, v38, v38
	v_mul_f32_e32 v249, v34, v34
	v_fmac_f32_e32 v248, v39, v39
	v_fmac_f32_e32 v249, v35, v35
	v_fmac_f32_e32 v248, v40, v40
	v_fmac_f32_e32 v249, v36, v36
	v_fmac_f32_e32 v248, v41, v41
	v_fmac_f32_e32 v249, v37, v37
	v_add_f32_e32 v248, v248, v249
	v_add_f32_e32 v252, v252, v248
	v_cvt_pk_bf16_f32 v228, v38, v39
	v_cvt_pk_bf16_f32 v229, v40, v41
	v_cvt_pk_bf16_f32 v230, v34, v35
	v_cvt_pk_bf16_f32 v231, v36, v37
	s_nop 1
	v_permlane16_swap_b32_e32 v228, v230
	v_permlane16_swap_b32_e32 v229, v231
	global_store_dwordx4 v253, v[228:231], s[8:9] offset:256
	ds_bpermute_b32 v248, v118, v252
	s_waitcnt lgkmcnt(0)
	v_add_f32_e32 v252, v252, v248
	ds_bpermute_b32 v248, v116, v252
	s_and_saveexec_b64 s[48:49], vcc
	s_cbranch_execz .Lepi5_g5
	s_waitcnt lgkmcnt(0)
	v_add_f32_e32 v252, v252, v248
	global_store_dword v[150:151], v252, off offset:1024
.Lepi5_g5:
	s_or_b64 exec, exec, s[48:49]
	s_waitcnt lgkmcnt(0)
	s_waitcnt vmcnt(14)
	v_permlane16_swap_b32_e32 v232, v234
	v_permlane16_swap_b32_e32 v233, v235
	v_lshlrev_b32_e32 v144, 16, v232
	v_and_b32_e32 v145, 0xffff0000, v232
	v_lshlrev_b32_e32 v146, 16, v233
	v_and_b32_e32 v147, 0xffff0000, v233
	v_pk_add_f32 v[30:31], v[30:31], v[144:145]
	v_pk_add_f32 v[32:33], v[32:33], v[146:147]
	v_lshlrev_b32_e32 v144, 16, v234
	v_and_b32_e32 v145, 0xffff0000, v234
	v_lshlrev_b32_e32 v146, 16, v235
	v_and_b32_e32 v147, 0xffff0000, v235
	v_pk_add_f32 v[26:27], v[26:27], v[144:145]
	v_pk_add_f32 v[28:29], v[28:29], v[146:147]
	v_mul_f32_e32 v248, v30, v30
	v_mul_f32_e32 v249, v26, v26
	v_fmac_f32_e32 v248, v31, v31
	v_fmac_f32_e32 v249, v27, v27
	v_fmac_f32_e32 v248, v32, v32
	v_fmac_f32_e32 v249, v28, v28
	v_fmac_f32_e32 v248, v33, v33
	v_fmac_f32_e32 v249, v29, v29
	v_add_f32_e32 v248, v248, v249
	v_mov_b32_e32 v252, v248
	v_cvt_pk_bf16_f32 v232, v30, v31
	v_cvt_pk_bf16_f32 v233, v32, v33
	v_cvt_pk_bf16_f32 v234, v26, v27
	v_cvt_pk_bf16_f32 v235, v28, v29
	s_nop 1
	v_permlane16_swap_b32_e32 v232, v234
	v_permlane16_swap_b32_e32 v233, v235
	v_add_u32_e32 v253, 0x50000, v250
	global_store_dwordx4 v253, v[232:235], s[8:9]
	s_waitcnt vmcnt(13)
	v_permlane16_swap_b32_e32 v236, v238
	v_permlane16_swap_b32_e32 v237, v239
	v_lshlrev_b32_e32 v144, 16, v236
	v_and_b32_e32 v145, 0xffff0000, v236
	v_lshlrev_b32_e32 v146, 16, v237
	v_and_b32_e32 v147, 0xffff0000, v237
	v_pk_add_f32 v[22:23], v[22:23], v[144:145]
	v_pk_add_f32 v[24:25], v[24:25], v[146:147]
	v_lshlrev_b32_e32 v144, 16, v238
	v_and_b32_e32 v145, 0xffff0000, v238
	v_lshlrev_b32_e32 v146, 16, v239
	v_and_b32_e32 v147, 0xffff0000, v239
	v_pk_add_f32 v[18:19], v[18:19], v[144:145]
	v_pk_add_f32 v[20:21], v[20:21], v[146:147]
	v_mul_f32_e32 v248, v22, v22
	v_mul_f32_e32 v249, v18, v18
	v_fmac_f32_e32 v248, v23, v23
	v_fmac_f32_e32 v249, v19, v19
	v_fmac_f32_e32 v248, v24, v24
	v_fmac_f32_e32 v249, v20, v20
	v_fmac_f32_e32 v248, v25, v25
	v_fmac_f32_e32 v249, v21, v21
	v_add_f32_e32 v248, v248, v249
	v_add_f32_e32 v252, v252, v248
	v_cvt_pk_bf16_f32 v236, v22, v23
	v_cvt_pk_bf16_f32 v237, v24, v25
	v_cvt_pk_bf16_f32 v238, v18, v19
	v_cvt_pk_bf16_f32 v239, v20, v21
	s_nop 1
	v_permlane16_swap_b32_e32 v236, v238
	v_permlane16_swap_b32_e32 v237, v239
	global_store_dwordx4 v253, v[236:239], s[8:9] offset:256
	ds_bpermute_b32 v248, v118, v252
	s_waitcnt lgkmcnt(0)
	v_add_f32_e32 v252, v252, v248
	ds_bpermute_b32 v248, v116, v252
	s_and_saveexec_b64 s[48:49], vcc
	s_cbranch_execz .Lepi5_g6
	s_waitcnt lgkmcnt(0)
	v_add_f32_e32 v252, v252, v248
	global_store_dword v[150:151], v252, off offset:2048
.Lepi5_g6:
	s_or_b64 exec, exec, s[48:49]
	s_waitcnt lgkmcnt(0)
	s_waitcnt vmcnt(12)
	v_permlane16_swap_b32_e32 v240, v242
	v_permlane16_swap_b32_e32 v241, v243
	v_lshlrev_b32_e32 v144, 16, v240
	v_and_b32_e32 v145, 0xffff0000, v240
	v_lshlrev_b32_e32 v146, 16, v241
	v_and_b32_e32 v147, 0xffff0000, v241
	v_pk_add_f32 v[14:15], v[14:15], v[144:145]
	v_pk_add_f32 v[16:17], v[16:17], v[146:147]
	v_lshlrev_b32_e32 v144, 16, v242
	v_and_b32_e32 v145, 0xffff0000, v242
	v_lshlrev_b32_e32 v146, 16, v243
	v_and_b32_e32 v147, 0xffff0000, v243
	v_pk_add_f32 v[10:11], v[10:11], v[144:145]
	v_pk_add_f32 v[12:13], v[12:13], v[146:147]
	v_mul_f32_e32 v248, v14, v14
	v_mul_f32_e32 v249, v10, v10
	v_fmac_f32_e32 v248, v15, v15
	v_fmac_f32_e32 v249, v11, v11
	v_fmac_f32_e32 v248, v16, v16
	v_fmac_f32_e32 v249, v12, v12
	v_fmac_f32_e32 v248, v17, v17
	v_fmac_f32_e32 v249, v13, v13
	v_add_f32_e32 v248, v248, v249
	v_mov_b32_e32 v252, v248
	v_cvt_pk_bf16_f32 v240, v14, v15
	v_cvt_pk_bf16_f32 v241, v16, v17
	v_cvt_pk_bf16_f32 v242, v10, v11
	v_cvt_pk_bf16_f32 v243, v12, v13
	s_nop 1
	v_permlane16_swap_b32_e32 v240, v242
	v_permlane16_swap_b32_e32 v241, v243
	v_add_u32_e32 v253, 0x58000, v250
	global_store_dwordx4 v253, v[240:243], s[8:9]
	s_waitcnt vmcnt(11)
	v_permlane16_swap_b32_e32 v244, v246
	v_permlane16_swap_b32_e32 v245, v247
	v_lshlrev_b32_e32 v144, 16, v244
	v_and_b32_e32 v145, 0xffff0000, v244
	v_lshlrev_b32_e32 v146, 16, v245
	v_and_b32_e32 v147, 0xffff0000, v245
	v_pk_add_f32 v[6:7], v[6:7], v[144:145]
	v_pk_add_f32 v[8:9], v[8:9], v[146:147]
	v_lshlrev_b32_e32 v144, 16, v246
	v_and_b32_e32 v145, 0xffff0000, v246
	v_lshlrev_b32_e32 v146, 16, v247
	v_and_b32_e32 v147, 0xffff0000, v247
	v_pk_add_f32 v[2:3], v[2:3], v[144:145]
	v_pk_add_f32 v[4:5], v[4:5], v[146:147]
	v_mul_f32_e32 v248, v6, v6
	v_mul_f32_e32 v249, v2, v2
	v_fmac_f32_e32 v248, v7, v7
	v_fmac_f32_e32 v249, v3, v3
	v_fmac_f32_e32 v248, v8, v8
	v_fmac_f32_e32 v249, v4, v4
	v_fmac_f32_e32 v248, v9, v9
	v_fmac_f32_e32 v249, v5, v5
	v_add_f32_e32 v248, v248, v249
	v_add_f32_e32 v252, v252, v248
	v_cvt_pk_bf16_f32 v244, v6, v7
	v_cvt_pk_bf16_f32 v245, v8, v9
	v_cvt_pk_bf16_f32 v246, v2, v3
	v_cvt_pk_bf16_f32 v247, v4, v5
	s_nop 1
	v_permlane16_swap_b32_e32 v244, v246
	v_permlane16_swap_b32_e32 v245, v247
	global_store_dwordx4 v253, v[244:247], s[8:9] offset:256
	ds_bpermute_b32 v248, v118, v252
	s_waitcnt lgkmcnt(0)
	v_add_f32_e32 v252, v252, v248
	ds_bpermute_b32 v248, v116, v252
	s_and_saveexec_b64 s[48:49], vcc
	s_cbranch_execz .LBB0_1899
	s_waitcnt lgkmcnt(0)
	v_add_f32_e32 v252, v252, v248
	global_store_dword v[150:151], v252, off offset:3072

.LBB0_2265:
	s_lshl_b32 s17, s42, 8
	v_mov_b32_e32 v152, v140
	v_mov_b32_e32 v153, v141
	s_or_b32 s17, s17, s62
	s_lshl_b32 s42, s42, 2
	v_lshl_add_u32 v136, v152, 2, s17
	s_lshl_b32 s17, s22, 8
	s_add_i32 s17, s17, s61
	v_add_u32_e32 v138, s17, v153
	v_ashrrev_i32_e32 v139, 31, v138
	v_lshlrev_b64 v[144:145], 11, v[138:139]
	v_ashrrev_i32_e32 v137, 31, v136
	v_lshl_add_u64 v[144:145], s[8:9], 0, v[144:145]
	v_lshl_add_u64 v[144:145], v[136:137], 1, v[144:145]
	v_and_b32_e32 v251, 1, v152
	v_lshlrev_b32_e32 v250, 11, v138
	v_mul_u32_u24_e32 v251, 24, v251
	v_lshl_add_u32 v250, v136, 1, v250
	v_add_u32_e32 v250, v250, v251
	global_load_dwordx4 v[216:219], v250, s[8:9]
	global_load_dwordx4 v[220:223], v250, s[8:9] offset:256
	v_add_u32_e32 v251, 0x8000, v250
	global_load_dwordx4 v[224:227], v251, s[8:9]
	global_load_dwordx4 v[228:231], v251, s[8:9] offset:256
	v_add_u32_e32 v251, 0x10000, v250
	global_load_dwordx4 v[232:235], v251, s[8:9]
	global_load_dwordx4 v[236:239], v251, s[8:9] offset:256
	v_add_u32_e32 v251, 0x18000, v250
	global_load_dwordx4 v[240:243], v251, s[8:9]
	global_load_dwordx4 v[244:247], v251, s[8:9] offset:256
	v_cmp_eq_u32_e32 vcc, 0, v152
	s_ashr_i32 s43, s42, 31
	v_lshlrev_b64 v[148:149], 6, v[138:139]
	v_lshl_add_u64 v[148:149], s[10:11], 0, v[148:149]
	v_lshl_add_u64 v[148:149], s[42:43], 2, v[148:149]
	s_lshl_b32 s22, s60, 2
	v_lshl_add_u64 v[148:149], v[148:149], 0, s[22:23]
	s_movk_i32 s22, 0x2000
	v_lshl_add_u64 v[150:151], v[148:149], 0, s[22:23]
	s_waitcnt vmcnt(7)
	v_permlane16_swap_b32_e32 v216, v218
	v_permlane16_swap_b32_e32 v217, v219
	v_lshlrev_b32_e32 v144, 16, v216
	v_and_b32_e32 v145, 0xffff0000, v216
	v_lshlrev_b32_e32 v146, 16, v217
	v_and_b32_e32 v147, 0xffff0000, v217
	v_pk_add_f32 v[126:127], v[126:127], v[144:145]
	v_pk_add_f32 v[128:129], v[128:129], v[146:147]
	v_lshlrev_b32_e32 v144, 16, v218
	v_and_b32_e32 v145, 0xffff0000, v218
	v_lshlrev_b32_e32 v146, 16, v219
	v_and_b32_e32 v147, 0xffff0000, v219
	v_pk_add_f32 v[122:123], v[122:123], v[144:145]
	v_pk_add_f32 v[124:125], v[124:125], v[146:147]
	v_mul_f32_e32 v248, v126, v126
	v_mul_f32_e32 v249, v122, v122
	v_fmac_f32_e32 v248, v127, v127
	v_fmac_f32_e32 v249, v123, v123
	v_fmac_f32_e32 v248, v128, v128
	v_fmac_f32_e32 v249, v124, v124
	v_fmac_f32_e32 v248, v129, v129
	v_fmac_f32_e32 v249, v125, v125
	v_add_f32_e32 v248, v248, v249
	v_mov_b32_e32 v252, v248
	v_cvt_pk_bf16_f32 v216, v126, v127
	v_cvt_pk_bf16_f32 v217, v128, v129
	v_cvt_pk_bf16_f32 v218, v122, v123
	v_cvt_pk_bf16_f32 v219, v124, v125
	s_nop 1
	v_permlane16_swap_b32_e32 v216, v218
	v_permlane16_swap_b32_e32 v217, v219
	global_store_dwordx4 v250, v[216:219], s[8:9]
	v_add_u32_e32 v251, 0x40000, v250
	s_nop 0
	global_load_dwordx4 v[216:219], v251, s[8:9]
	s_waitcnt vmcnt(8)
	v_permlane16_swap_b32_e32 v220, v222
	v_permlane16_swap_b32_e32 v221, v223
	v_lshlrev_b32_e32 v144, 16, v220
	v_and_b32_e32 v145, 0xffff0000, v220
	v_lshlrev_b32_e32 v146, 16, v221
	v_and_b32_e32 v147, 0xffff0000, v221
	v_pk_add_f32 v[118:119], v[118:119], v[144:145]
	v_pk_add_f32 v[120:121], v[120:121], v[146:147]
	v_lshlrev_b32_e32 v144, 16, v222
	v_and_b32_e32 v145, 0xffff0000, v222
	v_lshlrev_b32_e32 v146, 16, v223
	v_and_b32_e32 v147, 0xffff0000, v223
	v_pk_add_f32 v[114:115], v[114:115], v[144:145]
	v_pk_add_f32 v[116:117], v[116:117], v[146:147]
	v_mul_f32_e32 v248, v118, v118
	v_mul_f32_e32 v249, v114, v114
	v_fmac_f32_e32 v248, v119, v119
	v_fmac_f32_e32 v249, v115, v115
	v_fmac_f32_e32 v248, v120, v120
	v_fmac_f32_e32 v249, v116, v116
	v_fmac_f32_e32 v248, v121, v121
	v_fmac_f32_e32 v249, v117, v117
	v_add_f32_e32 v248, v248, v249
	v_add_f32_e32 v252, v252, v248
	v_cvt_pk_bf16_f32 v220, v118, v119
	v_cvt_pk_bf16_f32 v221, v120, v121
	v_cvt_pk_bf16_f32 v222, v114, v115
	v_cvt_pk_bf16_f32 v223, v116, v117
	s_nop 1
	v_permlane16_swap_b32_e32 v220, v222
	v_permlane16_swap_b32_e32 v221, v223
	global_store_dwordx4 v250, v[220:223], s[8:9] offset:256
	v_lshlrev_b32_e32 v118, 2, v153
	v_lshl_add_u32 v119, v152, 6, v118
	v_xor_b32_e32 v118, 64, v119
	v_xor_b32_e32 v116, 0x80, v119
	ds_bpermute_b32 v248, v118, v252
	s_waitcnt lgkmcnt(0)
	v_add_f32_e32 v252, v252, v248
	ds_bpermute_b32 v248, v116, v252
	s_nop 0
	global_load_dwordx4 v[220:223], v251, s[8:9] offset:256
	s_and_saveexec_b64 s[44:45], vcc
	s_cbranch_execz .Lepi11_g0
	s_waitcnt lgkmcnt(0)
	v_add_f32_e32 v252, v252, v248
	global_store_dword v[148:149], v252, off
.Lepi11_g0:
	s_or_b64 exec, exec, s[44:45]
	s_waitcnt lgkmcnt(0)
	s_waitcnt vmcnt(10)
	v_permlane16_swap_b32_e32 v224, v226
	v_permlane16_swap_b32_e32 v225, v227
	v_lshlrev_b32_e32 v144, 16, v224
	v_and_b32_e32 v145, 0xffff0000, v224
	v_lshlrev_b32_e32 v146, 16, v225
	v_and_b32_e32 v147, 0xffff0000, v225
	v_pk_add_f32 v[110:111], v[110:111], v[144:145]
	v_pk_add_f32 v[112:113], v[112:113], v[146:147]
	v_lshlrev_b32_e32 v144, 16, v226
	v_and_b32_e32 v145, 0xffff0000, v226
	v_lshlrev_b32_e32 v146, 16, v227
	v_and_b32_e32 v147, 0xffff0000, v227
	v_pk_add_f32 v[106:107], v[106:107], v[144:145]
	v_pk_add_f32 v[108:109], v[108:109], v[146:147]
	v_mul_f32_e32 v248, v110, v110
	v_mul_f32_e32 v249, v106, v106
	v_fmac_f32_e32 v248, v111, v111
	v_fmac_f32_e32 v249, v107, v107
	v_fmac_f32_e32 v248, v112, v112
	v_fmac_f32_e32 v249, v108, v108
	v_fmac_f32_e32 v248, v113, v113
	v_fmac_f32_e32 v249, v109, v109
	v_add_f32_e32 v248, v248, v249
	v_mov_b32_e32 v252, v248
	v_cvt_pk_bf16_f32 v224, v110, v111
	v_cvt_pk_bf16_f32 v225, v112, v113
	v_cvt_pk_bf16_f32 v226, v106, v107
	v_cvt_pk_bf16_f32 v227, v108, v109
	s_nop 1
	v_permlane16_swap_b32_e32 v224, v226
	v_permlane16_swap_b32_e32 v225, v227
	v_add_u32_e32 v253, 0x8000, v250
	global_store_dwordx4 v253, v[224:227], s[8:9]
	v_add_u32_e32 v251, 0x48000, v250
	s_nop 0
	global_load_dwordx4 v[224:227], v251, s[8:9]
	s_waitcnt vmcnt(11)
	v_permlane16_swap_b32_e32 v228, v230
	v_permlane16_swap_b32_e32 v229, v231
	v_lshlrev_b32_e32 v144, 16, v228
	v_and_b32_e32 v145, 0xffff0000, v228
	v_lshlrev_b32_e32 v146, 16, v229
	v_and_b32_e32 v147, 0xffff0000, v229
	v_pk_add_f32 v[102:103], v[102:103], v[144:145]
	v_pk_add_f32 v[104:105], v[104:105], v[146:147]
	v_lshlrev_b32_e32 v144, 16, v230
	v_and_b32_e32 v145, 0xffff0000, v230
	v_lshlrev_b32_e32 v146, 16, v231
	v_and_b32_e32 v147, 0xffff0000, v231
	v_pk_add_f32 v[98:99], v[98:99], v[144:145]
	v_pk_add_f32 v[100:101], v[100:101], v[146:147]
	v_mul_f32_e32 v248, v102, v102
	v_mul_f32_e32 v249, v98, v98
	v_fmac_f32_e32 v248, v103, v103
	v_fmac_f32_e32 v249, v99, v99
	v_fmac_f32_e32 v248, v104, v104
	v_fmac_f32_e32 v249, v100, v100
	v_fmac_f32_e32 v248, v105, v105
	v_fmac_f32_e32 v249, v101, v101
	v_add_f32_e32 v248, v248, v249
	v_add_f32_e32 v252, v252, v248
	v_cvt_pk_bf16_f32 v228, v102, v103
	v_cvt_pk_bf16_f32 v229, v104, v105
	v_cvt_pk_bf16_f32 v230, v98, v99
	v_cvt_pk_bf16_f32 v231, v100, v101
	s_nop 1
	v_permlane16_swap_b32_e32 v228, v230
	v_permlane16_swap_b32_e32 v229, v231
	global_store_dwordx4 v253, v[228:231], s[8:9] offset:256
	ds_bpermute_b32 v248, v118, v252
	s_waitcnt lgkmcnt(0)
	v_add_f32_e32 v252, v252, v248
	ds_bpermute_b32 v248, v116, v252
	s_nop 0
	global_load_dwordx4 v[228:231], v251, s[8:9] offset:256
	s_and_saveexec_b64 s[44:45], vcc
	s_cbranch_execz .Lepi11_g1
	s_waitcnt lgkmcnt(0)
	v_add_f32_e32 v252, v252, v248
	global_store_dword v[148:149], v252, off offset:1024
.Lepi11_g1:
	s_or_b64 exec, exec, s[44:45]
	s_waitcnt lgkmcnt(0)
	s_waitcnt vmcnt(13)
	v_permlane16_swap_b32_e32 v232, v234
	v_permlane16_swap_b32_e32 v233, v235
	v_lshlrev_b32_e32 v144, 16, v232
	v_and_b32_e32 v145, 0xffff0000, v232
	v_lshlrev_b32_e32 v146, 16, v233
	v_and_b32_e32 v147, 0xffff0000, v233
	v_pk_add_f32 v[94:95], v[94:95], v[144:145]
	v_pk_add_f32 v[96:97], v[96:97], v[146:147]
	v_lshlrev_b32_e32 v144, 16, v234
	v_and_b32_e32 v145, 0xffff0000, v234
	v_lshlrev_b32_e32 v146, 16, v235
	v_and_b32_e32 v147, 0xffff0000, v235
	v_pk_add_f32 v[90:91], v[90:91], v[144:145]
	v_pk_add_f32 v[92:93], v[92:93], v[146:147]
	v_mul_f32_e32 v248, v94, v94
	v_mul_f32_e32 v249, v90, v90
	v_fmac_f32_e32 v248, v95, v95
	v_fmac_f32_e32 v249, v91, v91
	v_fmac_f32_e32 v248, v96, v96
	v_fmac_f32_e32 v249, v92, v92
	v_fmac_f32_e32 v248, v97, v97
	v_fmac_f32_e32 v249, v93, v93
	v_add_f32_e32 v248, v248, v249
	v_mov_b32_e32 v252, v248
	v_cvt_pk_bf16_f32 v232, v94, v95
	v_cvt_pk_bf16_f32 v233, v96, v97
	v_cvt_pk_bf16_f32 v234, v90, v91
	v_cvt_pk_bf16_f32 v235, v92, v93
	s_nop 1
	v_permlane16_swap_b32_e32 v232, v234
	v_permlane16_swap_b32_e32 v233, v235
	v_add_u32_e32 v253, 0x10000, v250
	global_store_dwordx4 v253, v[232:235], s[8:9]
	v_add_u32_e32 v251, 0x50000, v250
	s_nop 0
	global_load_dwordx4 v[232:235], v251, s[8:9]
	s_waitcnt vmcnt(14)
	v_permlane16_swap_b32_e32 v236, v238
	v_permlane16_swap_b32_e32 v237, v239
	v_lshlrev_b32_e32 v144, 16, v236
	v_and_b32_e32 v145, 0xffff0000, v236
	v_lshlrev_b32_e32 v146, 16, v237
	v_and_b32_e32 v147, 0xffff0000, v237
	v_pk_add_f32 v[86:87], v[86:87], v[144:145]
	v_pk_add_f32 v[88:89], v[88:89], v[146:147]
	v_lshlrev_b32_e32 v144, 16, v238
	v_and_b32_e32 v145, 0xffff0000, v238
	v_lshlrev_b32_e32 v146, 16, v239
	v_and_b32_e32 v147, 0xffff0000, v239
	v_pk_add_f32 v[82:83], v[82:83], v[144:145]
	v_pk_add_f32 v[84:85], v[84:85], v[146:147]
	v_mul_f32_e32 v248, v86, v86
	v_mul_f32_e32 v249, v82, v82
	v_fmac_f32_e32 v248, v87, v87
	v_fmac_f32_e32 v249, v83, v83
	v_fmac_f32_e32 v248, v88, v88
	v_fmac_f32_e32 v249, v84, v84
	v_fmac_f32_e32 v248, v89, v89
	v_fmac_f32_e32 v249, v85, v85
	v_add_f32_e32 v248, v248, v249
	v_add_f32_e32 v252, v252, v248
	v_cvt_pk_bf16_f32 v236, v86, v87
	v_cvt_pk_bf16_f32 v237, v88, v89
	v_cvt_pk_bf16_f32 v238, v82, v83
	v_cvt_pk_bf16_f32 v239, v84, v85
	s_nop 1
	v_permlane16_swap_b32_e32 v236, v238
	v_permlane16_swap_b32_e32 v237, v239
	global_store_dwordx4 v253, v[236:239], s[8:9] offset:256
	ds_bpermute_b32 v248, v118, v252
	s_waitcnt lgkmcnt(0)
	v_add_f32_e32 v252, v252, v248
	ds_bpermute_b32 v248, v116, v252
	s_nop 0
	global_load_dwordx4 v[236:239], v251, s[8:9] offset:256
	s_and_saveexec_b64 s[44:45], vcc
	s_cbranch_execz .Lepi11_g2
	s_waitcnt lgkmcnt(0)
	v_add_f32_e32 v252, v252, v248
	global_store_dword v[148:149], v252, off offset:2048
.Lepi11_g2:
	s_or_b64 exec, exec, s[44:45]
	s_waitcnt lgkmcnt(0)
	s_waitcnt vmcnt(16)
	v_permlane16_swap_b32_e32 v240, v242
	v_permlane16_swap_b32_e32 v241, v243
	v_lshlrev_b32_e32 v144, 16, v240
	v_and_b32_e32 v145, 0xffff0000, v240
	v_lshlrev_b32_e32 v146, 16, v241
	v_and_b32_e32 v147, 0xffff0000, v241
	v_pk_add_f32 v[78:79], v[78:79], v[144:145]
	v_pk_add_f32 v[80:81], v[80:81], v[146:147]
	v_lshlrev_b32_e32 v144, 16, v242
	v_and_b32_e32 v145, 0xffff0000, v242
	v_lshlrev_b32_e32 v146, 16, v243
	v_and_b32_e32 v147, 0xffff0000, v243
	v_pk_add_f32 v[74:75], v[74:75], v[144:145]
	v_pk_add_f32 v[76:77], v[76:77], v[146:147]
	v_mul_f32_e32 v248, v78, v78
	v_mul_f32_e32 v249, v74, v74
	v_fmac_f32_e32 v248, v79, v79
	v_fmac_f32_e32 v249, v75, v75
	v_fmac_f32_e32 v248, v80, v80
	v_fmac_f32_e32 v249, v76, v76
	v_fmac_f32_e32 v248, v81, v81
	v_fmac_f32_e32 v249, v77, v77
	v_add_f32_e32 v248, v248, v249
	v_mov_b32_e32 v252, v248
	v_cvt_pk_bf16_f32 v240, v78, v79
	v_cvt_pk_bf16_f32 v241, v80, v81
	v_cvt_pk_bf16_f32 v242, v74, v75
	v_cvt_pk_bf16_f32 v243, v76, v77
	s_nop 1
	v_permlane16_swap_b32_e32 v240, v242
	v_permlane16_swap_b32_e32 v241, v243
	v_add_u32_e32 v253, 0x18000, v250
	global_store_dwordx4 v253, v[240:243], s[8:9]
	v_add_u32_e32 v251, 0x58000, v250
	s_nop 0
	global_load_dwordx4 v[240:243], v251, s[8:9]
	s_waitcnt vmcnt(17)
	v_permlane16_swap_b32_e32 v244, v246
	v_permlane16_swap_b32_e32 v245, v247
	v_lshlrev_b32_e32 v144, 16, v244
	v_and_b32_e32 v145, 0xffff0000, v244
	v_lshlrev_b32_e32 v146, 16, v245
	v_and_b32_e32 v147, 0xffff0000, v245
	v_pk_add_f32 v[70:71], v[70:71], v[144:145]
	v_pk_add_f32 v[72:73], v[72:73], v[146:147]
	v_lshlrev_b32_e32 v144, 16, v246
	v_and_b32_e32 v145, 0xffff0000, v246
	v_lshlrev_b32_e32 v146, 16, v247
	v_and_b32_e32 v147, 0xffff0000, v247
	v_pk_add_f32 v[66:67], v[66:67], v[144:145]
	v_pk_add_f32 v[68:69], v[68:69], v[146:147]
	v_mul_f32_e32 v248, v70, v70
	v_mul_f32_e32 v249, v66, v66
	v_fmac_f32_e32 v248, v71, v71
	v_fmac_f32_e32 v249, v67, v67
	v_fmac_f32_e32 v248, v72, v72
	v_fmac_f32_e32 v249, v68, v68
	v_fmac_f32_e32 v248, v73, v73
	v_fmac_f32_e32 v249, v69, v69
	v_add_f32_e32 v248, v248, v249
	v_add_f32_e32 v252, v252, v248
	v_cvt_pk_bf16_f32 v244, v70, v71
	v_cvt_pk_bf16_f32 v245, v72, v73
	v_cvt_pk_bf16_f32 v246, v66, v67
	v_cvt_pk_bf16_f32 v247, v68, v69
	s_nop 1
	v_permlane16_swap_b32_e32 v244, v246
	v_permlane16_swap_b32_e32 v245, v247
	global_store_dwordx4 v253, v[244:247], s[8:9] offset:256
	ds_bpermute_b32 v248, v118, v252
	s_waitcnt lgkmcnt(0)
	v_add_f32_e32 v252, v252, v248
	ds_bpermute_b32 v248, v116, v252
	s_nop 0
	global_load_dwordx4 v[244:247], v251, s[8:9] offset:256
	s_and_saveexec_b64 s[44:45], vcc
	s_cbranch_execz .Lepi11_g3
	s_waitcnt lgkmcnt(0)
	v_add_f32_e32 v252, v252, v248
	global_store_dword v[148:149], v252, off offset:3072
.Lepi11_g3:
	s_or_b64 exec, exec, s[44:45]
	s_waitcnt lgkmcnt(0)
	s_waitcnt vmcnt(18)
	v_permlane16_swap_b32_e32 v216, v218
	v_permlane16_swap_b32_e32 v217, v219
	v_lshlrev_b32_e32 v144, 16, v216
	v_and_b32_e32 v145, 0xffff0000, v216
	v_lshlrev_b32_e32 v146, 16, v217
	v_and_b32_e32 v147, 0xffff0000, v217
	v_pk_add_f32 v[62:63], v[62:63], v[144:145]
	v_pk_add_f32 v[64:65], v[64:65], v[146:147]
	v_lshlrev_b32_e32 v144, 16, v218
	v_and_b32_e32 v145, 0xffff0000, v218
	v_lshlrev_b32_e32 v146, 16, v219
	v_and_b32_e32 v147, 0xffff0000, v219
	v_pk_add_f32 v[58:59], v[58:59], v[144:145]
	v_pk_add_f32 v[60:61], v[60:61], v[146:147]
	v_mul_f32_e32 v248, v62, v62
	v_mul_f32_e32 v249, v58, v58
	v_fmac_f32_e32 v248, v63, v63
	v_fmac_f32_e32 v249, v59, v59
	v_fmac_f32_e32 v248, v64, v64
	v_fmac_f32_e32 v249, v60, v60
	v_fmac_f32_e32 v248, v65, v65
	v_fmac_f32_e32 v249, v61, v61
	v_add_f32_e32 v248, v248, v249
	v_mov_b32_e32 v252, v248
	v_cvt_pk_bf16_f32 v216, v62, v63
	v_cvt_pk_bf16_f32 v217, v64, v65
	v_cvt_pk_bf16_f32 v218, v58, v59
	v_cvt_pk_bf16_f32 v219, v60, v61
	s_nop 1
	v_permlane16_swap_b32_e32 v216, v218
	v_permlane16_swap_b32_e32 v217, v219
	v_add_u32_e32 v253, 0x40000, v250
	global_store_dwordx4 v253, v[216:219], s[8:9]
	s_waitcnt vmcnt(17)
	v_permlane16_swap_b32_e32 v220, v222
	v_permlane16_swap_b32_e32 v221, v223
	v_lshlrev_b32_e32 v144, 16, v220
	v_and_b32_e32 v145, 0xffff0000, v220
	v_lshlrev_b32_e32 v146, 16, v221
	v_and_b32_e32 v147, 0xffff0000, v221
	v_pk_add_f32 v[54:55], v[54:55], v[144:145]
	v_pk_add_f32 v[56:57], v[56:57], v[146:147]
	v_lshlrev_b32_e32 v144, 16, v222
	v_and_b32_e32 v145, 0xffff0000, v222
	v_lshlrev_b32_e32 v146, 16, v223
	v_and_b32_e32 v147, 0xffff0000, v223
	v_pk_add_f32 v[50:51], v[50:51], v[144:145]
	v_pk_add_f32 v[52:53], v[52:53], v[146:147]
	v_mul_f32_e32 v248, v54, v54
	v_mul_f32_e32 v249, v50, v50
	v_fmac_f32_e32 v248, v55, v55
	v_fmac_f32_e32 v249, v51, v51
	v_fmac_f32_e32 v248, v56, v56
	v_fmac_f32_e32 v249, v52, v52
	v_fmac_f32_e32 v248, v57, v57
	v_fmac_f32_e32 v249, v53, v53
	v_add_f32_e32 v248, v248, v249
	v_add_f32_e32 v252, v252, v248
	v_cvt_pk_bf16_f32 v220, v54, v55
	v_cvt_pk_bf16_f32 v221, v56, v57
	v_cvt_pk_bf16_f32 v222, v50, v51
	v_cvt_pk_bf16_f32 v223, v52, v53
	s_nop 1
	v_permlane16_swap_b32_e32 v220, v222
	v_permlane16_swap_b32_e32 v221, v223
	global_store_dwordx4 v253, v[220:223], s[8:9] offset:256
	ds_bpermute_b32 v248, v118, v252
	s_waitcnt lgkmcnt(0)
	v_add_f32_e32 v252, v252, v248
	ds_bpermute_b32 v248, v116, v252
	s_and_saveexec_b64 s[44:45], vcc
	s_cbranch_execz .Lepi11_g4
	s_waitcnt lgkmcnt(0)
	v_add_f32_e32 v252, v252, v248
	global_store_dword v[150:151], v252, off
.Lepi11_g4:
	s_or_b64 exec, exec, s[44:45]
	s_waitcnt lgkmcnt(0)
	s_waitcnt vmcnt(16)
	v_permlane16_swap_b32_e32 v224, v226
	v_permlane16_swap_b32_e32 v225, v227
	v_lshlrev_b32_e32 v144, 16, v224
	v_and_b32_e32 v145, 0xffff0000, v224
	v_lshlrev_b32_e32 v146, 16, v225
	v_and_b32_e32 v147, 0xffff0000, v225
	v_pk_add_f32 v[46:47], v[46:47], v[144:145]
	v_pk_add_f32 v[48:49], v[48:49], v[146:147]
	v_lshlrev_b32_e32 v144, 16, v226
	v_and_b32_e32 v145, 0xffff0000, v226
	v_lshlrev_b32_e32 v146, 16, v227
	v_and_b32_e32 v147, 0xffff0000, v227
	v_pk_add_f32 v[42:43], v[42:43], v[144:145]
	v_pk_add_f32 v[44:45], v[44:45], v[146:147]
	v_mul_f32_e32 v248, v46, v46
	v_mul_f32_e32 v249, v42, v42
	v_fmac_f32_e32 v248, v47, v47
	v_fmac_f32_e32 v249, v43, v43
	v_fmac_f32_e32 v248, v48, v48
	v_fmac_f32_e32 v249, v44, v44
	v_fmac_f32_e32 v248, v49, v49
	v_fmac_f32_e32 v249, v45, v45
	v_add_f32_e32 v248, v248, v249
	v_mov_b32_e32 v252, v248
	v_cvt_pk_bf16_f32 v224, v46, v47
	v_cvt_pk_bf16_f32 v225, v48, v49
	v_cvt_pk_bf16_f32 v226, v42, v43
	v_cvt_pk_bf16_f32 v227, v44, v45
	s_nop 1
	v_permlane16_swap_b32_e32 v224, v226
	v_permlane16_swap_b32_e32 v225, v227
	v_add_u32_e32 v253, 0x48000, v250
	global_store_dwordx4 v253, v[224:227], s[8:9]
	s_waitcnt vmcnt(15)
	v_permlane16_swap_b32_e32 v228, v230
	v_permlane16_swap_b32_e32 v229, v231
	v_lshlrev_b32_e32 v144, 16, v228
	v_and_b32_e32 v145, 0xffff0000, v228
	v_lshlrev_b32_e32 v146, 16, v229
	v_and_b32_e32 v147, 0xffff0000, v229
	v_pk_add_f32 v[38:39], v[38:39], v[144:145]
	v_pk_add_f32 v[40:41], v[40:41], v[146:147]
	v_lshlrev_b32_e32 v144, 16, v230
	v_and_b32_e32 v145, 0xffff0000, v230
	v_lshlrev_b32_e32 v146, 16, v231
	v_and_b32_e32 v147, 0xffff0000, v231
	v_pk_add_f32 v[34:35], v[34:35], v[144:145]
	v_pk_add_f32 v[36:37], v[36:37], v[146:147]
	v_mul_f32_e32 v248, v38, v38
	v_mul_f32_e32 v249, v34, v34
	v_fmac_f32_e32 v248, v39, v39
	v_fmac_f32_e32 v249, v35, v35
	v_fmac_f32_e32 v248, v40, v40
	v_fmac_f32_e32 v249, v36, v36
	v_fmac_f32_e32 v248, v41, v41
	v_fmac_f32_e32 v249, v37, v37
	v_add_f32_e32 v248, v248, v249
	v_add_f32_e32 v252, v252, v248
	v_cvt_pk_bf16_f32 v228, v38, v39
	v_cvt_pk_bf16_f32 v229, v40, v41
	v_cvt_pk_bf16_f32 v230, v34, v35
	v_cvt_pk_bf16_f32 v231, v36, v37
	s_nop 1
	v_permlane16_swap_b32_e32 v228, v230
	v_permlane16_swap_b32_e32 v229, v231
	global_store_dwordx4 v253, v[228:231], s[8:9] offset:256
	ds_bpermute_b32 v248, v118, v252
	s_waitcnt lgkmcnt(0)
	v_add_f32_e32 v252, v252, v248
	ds_bpermute_b32 v248, v116, v252
	s_and_saveexec_b64 s[44:45], vcc
	s_cbranch_execz .Lepi11_g5
	s_waitcnt lgkmcnt(0)
	v_add_f32_e32 v252, v252, v248
	global_store_dword v[150:151], v252, off offset:1024
.Lepi11_g5:
	s_or_b64 exec, exec, s[44:45]
	s_waitcnt lgkmcnt(0)
	s_waitcnt vmcnt(14)
	v_permlane16_swap_b32_e32 v232, v234
	v_permlane16_swap_b32_e32 v233, v235
	v_lshlrev_b32_e32 v144, 16, v232
	v_and_b32_e32 v145, 0xffff0000, v232
	v_lshlrev_b32_e32 v146, 16, v233
	v_and_b32_e32 v147, 0xffff0000, v233
	v_pk_add_f32 v[30:31], v[30:31], v[144:145]
	v_pk_add_f32 v[32:33], v[32:33], v[146:147]
	v_lshlrev_b32_e32 v144, 16, v234
	v_and_b32_e32 v145, 0xffff0000, v234
	v_lshlrev_b32_e32 v146, 16, v235
	v_and_b32_e32 v147, 0xffff0000, v235
	v_pk_add_f32 v[26:27], v[26:27], v[144:145]
	v_pk_add_f32 v[28:29], v[28:29], v[146:147]
	v_mul_f32_e32 v248, v30, v30
	v_mul_f32_e32 v249, v26, v26
	v_fmac_f32_e32 v248, v31, v31
	v_fmac_f32_e32 v249, v27, v27
	v_fmac_f32_e32 v248, v32, v32
	v_fmac_f32_e32 v249, v28, v28
	v_fmac_f32_e32 v248, v33, v33
	v_fmac_f32_e32 v249, v29, v29
	v_add_f32_e32 v248, v248, v249
	v_mov_b32_e32 v252, v248
	v_cvt_pk_bf16_f32 v232, v30, v31
	v_cvt_pk_bf16_f32 v233, v32, v33
	v_cvt_pk_bf16_f32 v234, v26, v27
	v_cvt_pk_bf16_f32 v235, v28, v29
	s_nop 1
	v_permlane16_swap_b32_e32 v232, v234
	v_permlane16_swap_b32_e32 v233, v235
	v_add_u32_e32 v253, 0x50000, v250
	global_store_dwordx4 v253, v[232:235], s[8:9]
	s_waitcnt vmcnt(13)
	v_permlane16_swap_b32_e32 v236, v238
	v_permlane16_swap_b32_e32 v237, v239
	v_lshlrev_b32_e32 v144, 16, v236
	v_and_b32_e32 v145, 0xffff0000, v236
	v_lshlrev_b32_e32 v146, 16, v237
	v_and_b32_e32 v147, 0xffff0000, v237
	v_pk_add_f32 v[22:23], v[22:23], v[144:145]
	v_pk_add_f32 v[24:25], v[24:25], v[146:147]
	v_lshlrev_b32_e32 v144, 16, v238
	v_and_b32_e32 v145, 0xffff0000, v238
	v_lshlrev_b32_e32 v146, 16, v239
	v_and_b32_e32 v147, 0xffff0000, v239
	v_pk_add_f32 v[18:19], v[18:19], v[144:145]
	v_pk_add_f32 v[20:21], v[20:21], v[146:147]
	v_mul_f32_e32 v248, v22, v22
	v_mul_f32_e32 v249, v18, v18
	v_fmac_f32_e32 v248, v23, v23
	v_fmac_f32_e32 v249, v19, v19
	v_fmac_f32_e32 v248, v24, v24
	v_fmac_f32_e32 v249, v20, v20
	v_fmac_f32_e32 v248, v25, v25
	v_fmac_f32_e32 v249, v21, v21
	v_add_f32_e32 v248, v248, v249
	v_add_f32_e32 v252, v252, v248
	v_cvt_pk_bf16_f32 v236, v22, v23
	v_cvt_pk_bf16_f32 v237, v24, v25
	v_cvt_pk_bf16_f32 v238, v18, v19
	v_cvt_pk_bf16_f32 v239, v20, v21
	s_nop 1
	v_permlane16_swap_b32_e32 v236, v238
	v_permlane16_swap_b32_e32 v237, v239
	global_store_dwordx4 v253, v[236:239], s[8:9] offset:256
	ds_bpermute_b32 v248, v118, v252
	s_waitcnt lgkmcnt(0)
	v_add_f32_e32 v252, v252, v248
	ds_bpermute_b32 v248, v116, v252
	s_and_saveexec_b64 s[44:45], vcc
	s_cbranch_execz .Lepi11_g6
	s_waitcnt lgkmcnt(0)
	v_add_f32_e32 v252, v252, v248
	global_store_dword v[150:151], v252, off offset:2048
.Lepi11_g6:
	s_or_b64 exec, exec, s[44:45]
	s_waitcnt lgkmcnt(0)
	s_waitcnt vmcnt(12)
	v_permlane16_swap_b32_e32 v240, v242
	v_permlane16_swap_b32_e32 v241, v243
	v_lshlrev_b32_e32 v144, 16, v240
	v_and_b32_e32 v145, 0xffff0000, v240
	v_lshlrev_b32_e32 v146, 16, v241
	v_and_b32_e32 v147, 0xffff0000, v241
	v_pk_add_f32 v[14:15], v[14:15], v[144:145]
	v_pk_add_f32 v[16:17], v[16:17], v[146:147]
	v_lshlrev_b32_e32 v144, 16, v242
	v_and_b32_e32 v145, 0xffff0000, v242
	v_lshlrev_b32_e32 v146, 16, v243
	v_and_b32_e32 v147, 0xffff0000, v243
	v_pk_add_f32 v[10:11], v[10:11], v[144:145]
	v_pk_add_f32 v[12:13], v[12:13], v[146:147]
	v_mul_f32_e32 v248, v14, v14
	v_mul_f32_e32 v249, v10, v10
	v_fmac_f32_e32 v248, v15, v15
	v_fmac_f32_e32 v249, v11, v11
	v_fmac_f32_e32 v248, v16, v16
	v_fmac_f32_e32 v249, v12, v12
	v_fmac_f32_e32 v248, v17, v17
	v_fmac_f32_e32 v249, v13, v13
	v_add_f32_e32 v248, v248, v249
	v_mov_b32_e32 v252, v248
	v_cvt_pk_bf16_f32 v240, v14, v15
	v_cvt_pk_bf16_f32 v241, v16, v17
	v_cvt_pk_bf16_f32 v242, v10, v11
	v_cvt_pk_bf16_f32 v243, v12, v13
	s_nop 1
	v_permlane16_swap_b32_e32 v240, v242
	v_permlane16_swap_b32_e32 v241, v243
	v_add_u32_e32 v253, 0x58000, v250
	global_store_dwordx4 v253, v[240:243], s[8:9]
	s_waitcnt vmcnt(11)
	v_permlane16_swap_b32_e32 v244, v246
	v_permlane16_swap_b32_e32 v245, v247
	v_lshlrev_b32_e32 v144, 16, v244
	v_and_b32_e32 v145, 0xffff0000, v244
	v_lshlrev_b32_e32 v146, 16, v245
	v_and_b32_e32 v147, 0xffff0000, v245
	v_pk_add_f32 v[6:7], v[6:7], v[144:145]
	v_pk_add_f32 v[8:9], v[8:9], v[146:147]
	v_lshlrev_b32_e32 v144, 16, v246
	v_and_b32_e32 v145, 0xffff0000, v246
	v_lshlrev_b32_e32 v146, 16, v247
	v_and_b32_e32 v147, 0xffff0000, v247
	v_pk_add_f32 v[2:3], v[2:3], v[144:145]
	v_pk_add_f32 v[4:5], v[4:5], v[146:147]
	v_mul_f32_e32 v248, v6, v6
	v_mul_f32_e32 v249, v2, v2
	v_fmac_f32_e32 v248, v7, v7
	v_fmac_f32_e32 v249, v3, v3
	v_fmac_f32_e32 v248, v8, v8
	v_fmac_f32_e32 v249, v4, v4
	v_fmac_f32_e32 v248, v9, v9
	v_fmac_f32_e32 v249, v5, v5
	v_add_f32_e32 v248, v248, v249
	v_add_f32_e32 v252, v252, v248
	v_cvt_pk_bf16_f32 v244, v6, v7
	v_cvt_pk_bf16_f32 v245, v8, v9
	v_cvt_pk_bf16_f32 v246, v2, v3
	v_cvt_pk_bf16_f32 v247, v4, v5
	s_nop 1
	v_permlane16_swap_b32_e32 v244, v246
	v_permlane16_swap_b32_e32 v245, v247
	global_store_dwordx4 v253, v[244:247], s[8:9] offset:256
	ds_bpermute_b32 v248, v118, v252
	s_waitcnt lgkmcnt(0)
	v_add_f32_e32 v252, v252, v248
	ds_bpermute_b32 v248, v116, v252
	s_and_saveexec_b64 s[44:45], vcc
	s_cbranch_execz .LBB0_2281
	s_waitcnt lgkmcnt(0)
	v_add_f32_e32 v252, v252, v248
	global_store_dword v[150:151], v252, off offset:3072

.LBB0_2543:
	s_lshl_b32 s4, s46, 8
	v_mov_b32_e32 v152, v140
	v_mov_b32_e32 v153, v141
	s_or_b32 s4, s4, s64
	s_nop 0
	v_lshl_add_u32 v136, v152, 2, s4
	s_lshl_b32 s4, s22, 8
	s_add_i32 s4, s4, s63
	v_add_u32_e32 v138, s4, v153
	v_ashrrev_i32_e32 v139, 31, v138
	v_ashrrev_i32_e32 v137, 31, v136
	v_lshlrev_b64 v[144:145], 10, v[138:139]
	v_lshl_add_u64 v[144:145], v[144:145], 0, v[136:137]
	v_lshlrev_b64 v[144:145], 1, v[144:145]
	v_lshl_add_u64 v[146:147], s[8:9], 0, v[144:145]
	v_and_b32_e32 v251, 1, v152
	v_lshlrev_b32_e32 v250, 11, v138
	v_mul_u32_u24_e32 v251, 24, v251
	v_lshl_add_u32 v250, v136, 1, v250
	v_add_u32_e32 v250, v250, v251
	global_load_dwordx4 v[216:219], v250, s[8:9]
	global_load_dwordx4 v[220:223], v250, s[8:9] offset:256
	v_add_u32_e32 v251, 0x8000, v250
	global_load_dwordx4 v[224:227], v251, s[8:9]
	global_load_dwordx4 v[228:231], v251, s[8:9] offset:256
	v_add_u32_e32 v251, 0x10000, v250
	global_load_dwordx4 v[232:235], v251, s[8:9]
	global_load_dwordx4 v[236:239], v251, s[8:9] offset:256
	v_add_u32_e32 v251, 0x18000, v250
	global_load_dwordx4 v[240:243], v251, s[8:9]
	global_load_dwordx4 v[244:247], v251, s[8:9] offset:256
	v_lshl_add_u64 v[144:145], s[16:17], 0, v[144:145]
	s_lshl_b32 s4, s46, 2
	v_cmp_eq_u32_e32 vcc, 0, v152
	s_ashr_i32 s5, s4, 31
	v_lshlrev_b64 v[148:149], 6, v[138:139]
	v_lshl_add_u64 v[148:149], s[10:11], 0, v[148:149]
	v_lshl_add_u64 v[148:149], s[4:5], 2, v[148:149]
	s_lshl_b32 s22, s62, 2
	v_lshl_add_u64 v[148:149], v[148:149], 0, s[22:23]
	s_movk_i32 s22, 0x2000
	v_lshl_add_u64 v[150:151], v[148:149], 0, s[22:23]
	s_waitcnt vmcnt(7)
	v_permlane16_swap_b32_e32 v216, v218
	v_permlane16_swap_b32_e32 v217, v219
	v_lshlrev_b32_e32 v144, 16, v216
	v_and_b32_e32 v145, 0xffff0000, v216
	v_lshlrev_b32_e32 v146, 16, v217
	v_and_b32_e32 v147, 0xffff0000, v217
	v_pk_add_f32 v[126:127], v[126:127], v[144:145]
	v_pk_add_f32 v[128:129], v[128:129], v[146:147]
	v_lshlrev_b32_e32 v144, 16, v218
	v_and_b32_e32 v145, 0xffff0000, v218
	v_lshlrev_b32_e32 v146, 16, v219
	v_and_b32_e32 v147, 0xffff0000, v219
	v_pk_add_f32 v[122:123], v[122:123], v[144:145]
	v_pk_add_f32 v[124:125], v[124:125], v[146:147]
	v_mul_f32_e32 v248, v126, v126
	v_mul_f32_e32 v249, v122, v122
	v_fmac_f32_e32 v248, v127, v127
	v_fmac_f32_e32 v249, v123, v123
	v_fmac_f32_e32 v248, v128, v128
	v_fmac_f32_e32 v249, v124, v124
	v_fmac_f32_e32 v248, v129, v129
	v_fmac_f32_e32 v249, v125, v125
	v_add_f32_e32 v248, v248, v249
	v_mov_b32_e32 v252, v248
	v_cvt_pk_bf16_f32 v216, v126, v127
	v_cvt_pk_bf16_f32 v217, v128, v129
	v_cvt_pk_bf16_f32 v218, v122, v123
	v_cvt_pk_bf16_f32 v219, v124, v125
	s_nop 1
	v_permlane16_swap_b32_e32 v216, v218
	v_permlane16_swap_b32_e32 v217, v219
	global_store_dwordx4 v250, v[216:219], s[16:17]
	v_add_u32_e32 v251, 0x40000, v250
	s_nop 0
	global_load_dwordx4 v[216:219], v251, s[8:9]
	s_waitcnt vmcnt(8)
	v_permlane16_swap_b32_e32 v220, v222
	v_permlane16_swap_b32_e32 v221, v223
	v_lshlrev_b32_e32 v144, 16, v220
	v_and_b32_e32 v145, 0xffff0000, v220
	v_lshlrev_b32_e32 v146, 16, v221
	v_and_b32_e32 v147, 0xffff0000, v221
	v_pk_add_f32 v[118:119], v[118:119], v[144:145]
	v_pk_add_f32 v[120:121], v[120:121], v[146:147]
	v_lshlrev_b32_e32 v144, 16, v222
	v_and_b32_e32 v145, 0xffff0000, v222
	v_lshlrev_b32_e32 v146, 16, v223
	v_and_b32_e32 v147, 0xffff0000, v223
	v_pk_add_f32 v[114:115], v[114:115], v[144:145]
	v_pk_add_f32 v[116:117], v[116:117], v[146:147]
	v_mul_f32_e32 v248, v118, v118
	v_mul_f32_e32 v249, v114, v114
	v_fmac_f32_e32 v248, v119, v119
	v_fmac_f32_e32 v249, v115, v115
	v_fmac_f32_e32 v248, v120, v120
	v_fmac_f32_e32 v249, v116, v116
	v_fmac_f32_e32 v248, v121, v121
	v_fmac_f32_e32 v249, v117, v117
	v_add_f32_e32 v248, v248, v249
	v_add_f32_e32 v252, v252, v248
	v_cvt_pk_bf16_f32 v220, v118, v119
	v_cvt_pk_bf16_f32 v221, v120, v121
	v_cvt_pk_bf16_f32 v222, v114, v115
	v_cvt_pk_bf16_f32 v223, v116, v117
	s_nop 1
	v_permlane16_swap_b32_e32 v220, v222
	v_permlane16_swap_b32_e32 v221, v223
	global_store_dwordx4 v250, v[220:223], s[16:17] offset:256
	v_lshlrev_b32_e32 v118, 2, v153
	v_lshl_add_u32 v119, v152, 6, v118
	v_xor_b32_e32 v118, 64, v119
	v_xor_b32_e32 v116, 0x80, v119
	ds_bpermute_b32 v248, v118, v252
	s_waitcnt lgkmcnt(0)
	v_add_f32_e32 v252, v252, v248
	ds_bpermute_b32 v248, v116, v252
	s_nop 0
	global_load_dwordx4 v[220:223], v251, s[8:9] offset:256
	s_and_saveexec_b64 s[46:47], vcc
	s_cbranch_execz .Lepi14_g0
	s_waitcnt lgkmcnt(0)
	v_add_f32_e32 v252, v252, v248
	global_store_dword v[148:149], v252, off
.Lepi14_g0:
	s_or_b64 exec, exec, s[46:47]
	s_waitcnt lgkmcnt(0)
	s_waitcnt vmcnt(10)
	v_permlane16_swap_b32_e32 v224, v226
	v_permlane16_swap_b32_e32 v225, v227
	v_lshlrev_b32_e32 v144, 16, v224
	v_and_b32_e32 v145, 0xffff0000, v224
	v_lshlrev_b32_e32 v146, 16, v225
	v_and_b32_e32 v147, 0xffff0000, v225
	v_pk_add_f32 v[110:111], v[110:111], v[144:145]
	v_pk_add_f32 v[112:113], v[112:113], v[146:147]
	v_lshlrev_b32_e32 v144, 16, v226
	v_and_b32_e32 v145, 0xffff0000, v226
	v_lshlrev_b32_e32 v146, 16, v227
	v_and_b32_e32 v147, 0xffff0000, v227
	v_pk_add_f32 v[106:107], v[106:107], v[144:145]
	v_pk_add_f32 v[108:109], v[108:109], v[146:147]
	v_mul_f32_e32 v248, v110, v110
	v_mul_f32_e32 v249, v106, v106
	v_fmac_f32_e32 v248, v111, v111
	v_fmac_f32_e32 v249, v107, v107
	v_fmac_f32_e32 v248, v112, v112
	v_fmac_f32_e32 v249, v108, v108
	v_fmac_f32_e32 v248, v113, v113
	v_fmac_f32_e32 v249, v109, v109
	v_add_f32_e32 v248, v248, v249
	v_mov_b32_e32 v252, v248
	v_cvt_pk_bf16_f32 v224, v110, v111
	v_cvt_pk_bf16_f32 v225, v112, v113
	v_cvt_pk_bf16_f32 v226, v106, v107
	v_cvt_pk_bf16_f32 v227, v108, v109
	s_nop 1
	v_permlane16_swap_b32_e32 v224, v226
	v_permlane16_swap_b32_e32 v225, v227
	v_add_u32_e32 v253, 0x8000, v250
	global_store_dwordx4 v253, v[224:227], s[16:17]
	v_add_u32_e32 v251, 0x48000, v250
	s_nop 0
	global_load_dwordx4 v[224:227], v251, s[8:9]
	s_waitcnt vmcnt(11)
	v_permlane16_swap_b32_e32 v228, v230
	v_permlane16_swap_b32_e32 v229, v231
	v_lshlrev_b32_e32 v144, 16, v228
	v_and_b32_e32 v145, 0xffff0000, v228
	v_lshlrev_b32_e32 v146, 16, v229
	v_and_b32_e32 v147, 0xffff0000, v229
	v_pk_add_f32 v[102:103], v[102:103], v[144:145]
	v_pk_add_f32 v[104:105], v[104:105], v[146:147]
	v_lshlrev_b32_e32 v144, 16, v230
	v_and_b32_e32 v145, 0xffff0000, v230
	v_lshlrev_b32_e32 v146, 16, v231
	v_and_b32_e32 v147, 0xffff0000, v231
	v_pk_add_f32 v[98:99], v[98:99], v[144:145]
	v_pk_add_f32 v[100:101], v[100:101], v[146:147]
	v_mul_f32_e32 v248, v102, v102
	v_mul_f32_e32 v249, v98, v98
	v_fmac_f32_e32 v248, v103, v103
	v_fmac_f32_e32 v249, v99, v99
	v_fmac_f32_e32 v248, v104, v104
	v_fmac_f32_e32 v249, v100, v100
	v_fmac_f32_e32 v248, v105, v105
	v_fmac_f32_e32 v249, v101, v101
	v_add_f32_e32 v248, v248, v249
	v_add_f32_e32 v252, v252, v248
	v_cvt_pk_bf16_f32 v228, v102, v103
	v_cvt_pk_bf16_f32 v229, v104, v105
	v_cvt_pk_bf16_f32 v230, v98, v99
	v_cvt_pk_bf16_f32 v231, v100, v101
	s_nop 1
	v_permlane16_swap_b32_e32 v228, v230
	v_permlane16_swap_b32_e32 v229, v231
	global_store_dwordx4 v253, v[228:231], s[16:17] offset:256
	ds_bpermute_b32 v248, v118, v252
	s_waitcnt lgkmcnt(0)
	v_add_f32_e32 v252, v252, v248
	ds_bpermute_b32 v248, v116, v252
	s_nop 0
	global_load_dwordx4 v[228:231], v251, s[8:9] offset:256
	s_and_saveexec_b64 s[46:47], vcc
	s_cbranch_execz .Lepi14_g1
	s_waitcnt lgkmcnt(0)
	v_add_f32_e32 v252, v252, v248
	global_store_dword v[148:149], v252, off offset:1024
.Lepi14_g1:
	s_or_b64 exec, exec, s[46:47]
	s_waitcnt lgkmcnt(0)
	s_waitcnt vmcnt(13)
	v_permlane16_swap_b32_e32 v232, v234
	v_permlane16_swap_b32_e32 v233, v235
	v_lshlrev_b32_e32 v144, 16, v232
	v_and_b32_e32 v145, 0xffff0000, v232
	v_lshlrev_b32_e32 v146, 16, v233
	v_and_b32_e32 v147, 0xffff0000, v233
	v_pk_add_f32 v[94:95], v[94:95], v[144:145]
	v_pk_add_f32 v[96:97], v[96:97], v[146:147]
	v_lshlrev_b32_e32 v144, 16, v234
	v_and_b32_e32 v145, 0xffff0000, v234
	v_lshlrev_b32_e32 v146, 16, v235
	v_and_b32_e32 v147, 0xffff0000, v235
	v_pk_add_f32 v[90:91], v[90:91], v[144:145]
	v_pk_add_f32 v[92:93], v[92:93], v[146:147]
	v_mul_f32_e32 v248, v94, v94
	v_mul_f32_e32 v249, v90, v90
	v_fmac_f32_e32 v248, v95, v95
	v_fmac_f32_e32 v249, v91, v91
	v_fmac_f32_e32 v248, v96, v96
	v_fmac_f32_e32 v249, v92, v92
	v_fmac_f32_e32 v248, v97, v97
	v_fmac_f32_e32 v249, v93, v93
	v_add_f32_e32 v248, v248, v249
	v_mov_b32_e32 v252, v248
	v_cvt_pk_bf16_f32 v232, v94, v95
	v_cvt_pk_bf16_f32 v233, v96, v97
	v_cvt_pk_bf16_f32 v234, v90, v91
	v_cvt_pk_bf16_f32 v235, v92, v93
	s_nop 1
	v_permlane16_swap_b32_e32 v232, v234
	v_permlane16_swap_b32_e32 v233, v235
	v_add_u32_e32 v253, 0x10000, v250
	global_store_dwordx4 v253, v[232:235], s[16:17]
	v_add_u32_e32 v251, 0x50000, v250
	s_nop 0
	global_load_dwordx4 v[232:235], v251, s[8:9]
	s_waitcnt vmcnt(14)
	v_permlane16_swap_b32_e32 v236, v238
	v_permlane16_swap_b32_e32 v237, v239
	v_lshlrev_b32_e32 v144, 16, v236
	v_and_b32_e32 v145, 0xffff0000, v236
	v_lshlrev_b32_e32 v146, 16, v237
	v_and_b32_e32 v147, 0xffff0000, v237
	v_pk_add_f32 v[86:87], v[86:87], v[144:145]
	v_pk_add_f32 v[88:89], v[88:89], v[146:147]
	v_lshlrev_b32_e32 v144, 16, v238
	v_and_b32_e32 v145, 0xffff0000, v238
	v_lshlrev_b32_e32 v146, 16, v239
	v_and_b32_e32 v147, 0xffff0000, v239
	v_pk_add_f32 v[82:83], v[82:83], v[144:145]
	v_pk_add_f32 v[84:85], v[84:85], v[146:147]
	v_mul_f32_e32 v248, v86, v86
	v_mul_f32_e32 v249, v82, v82
	v_fmac_f32_e32 v248, v87, v87
	v_fmac_f32_e32 v249, v83, v83
	v_fmac_f32_e32 v248, v88, v88
	v_fmac_f32_e32 v249, v84, v84
	v_fmac_f32_e32 v248, v89, v89
	v_fmac_f32_e32 v249, v85, v85
	v_add_f32_e32 v248, v248, v249
	v_add_f32_e32 v252, v252, v248
	v_cvt_pk_bf16_f32 v236, v86, v87
	v_cvt_pk_bf16_f32 v237, v88, v89
	v_cvt_pk_bf16_f32 v238, v82, v83
	v_cvt_pk_bf16_f32 v239, v84, v85
	s_nop 1
	v_permlane16_swap_b32_e32 v236, v238
	v_permlane16_swap_b32_e32 v237, v239
	global_store_dwordx4 v253, v[236:239], s[16:17] offset:256
	ds_bpermute_b32 v248, v118, v252
	s_waitcnt lgkmcnt(0)
	v_add_f32_e32 v252, v252, v248
	ds_bpermute_b32 v248, v116, v252
	s_nop 0
	global_load_dwordx4 v[236:239], v251, s[8:9] offset:256
	s_and_saveexec_b64 s[46:47], vcc
	s_cbranch_execz .Lepi14_g2
	s_waitcnt lgkmcnt(0)
	v_add_f32_e32 v252, v252, v248
	global_store_dword v[148:149], v252, off offset:2048
.Lepi14_g2:
	s_or_b64 exec, exec, s[46:47]
	s_waitcnt lgkmcnt(0)
	s_waitcnt vmcnt(16)
	v_permlane16_swap_b32_e32 v240, v242
	v_permlane16_swap_b32_e32 v241, v243
	v_lshlrev_b32_e32 v144, 16, v240
	v_and_b32_e32 v145, 0xffff0000, v240
	v_lshlrev_b32_e32 v146, 16, v241
	v_and_b32_e32 v147, 0xffff0000, v241
	v_pk_add_f32 v[78:79], v[78:79], v[144:145]
	v_pk_add_f32 v[80:81], v[80:81], v[146:147]
	v_lshlrev_b32_e32 v144, 16, v242
	v_and_b32_e32 v145, 0xffff0000, v242
	v_lshlrev_b32_e32 v146, 16, v243
	v_and_b32_e32 v147, 0xffff0000, v243
	v_pk_add_f32 v[74:75], v[74:75], v[144:145]
	v_pk_add_f32 v[76:77], v[76:77], v[146:147]
	v_mul_f32_e32 v248, v78, v78
	v_mul_f32_e32 v249, v74, v74
	v_fmac_f32_e32 v248, v79, v79
	v_fmac_f32_e32 v249, v75, v75
	v_fmac_f32_e32 v248, v80, v80
	v_fmac_f32_e32 v249, v76, v76
	v_fmac_f32_e32 v248, v81, v81
	v_fmac_f32_e32 v249, v77, v77
	v_add_f32_e32 v248, v248, v249
	v_mov_b32_e32 v252, v248
	v_cvt_pk_bf16_f32 v240, v78, v79
	v_cvt_pk_bf16_f32 v241, v80, v81
	v_cvt_pk_bf16_f32 v242, v74, v75
	v_cvt_pk_bf16_f32 v243, v76, v77
	s_nop 1
	v_permlane16_swap_b32_e32 v240, v242
	v_permlane16_swap_b32_e32 v241, v243
	v_add_u32_e32 v253, 0x18000, v250
	global_store_dwordx4 v253, v[240:243], s[16:17]
	v_add_u32_e32 v251, 0x58000, v250
	s_nop 0
	global_load_dwordx4 v[240:243], v251, s[8:9]
	s_waitcnt vmcnt(17)
	v_permlane16_swap_b32_e32 v244, v246
	v_permlane16_swap_b32_e32 v245, v247
	v_lshlrev_b32_e32 v144, 16, v244
	v_and_b32_e32 v145, 0xffff0000, v244
	v_lshlrev_b32_e32 v146, 16, v245
	v_and_b32_e32 v147, 0xffff0000, v245
	v_pk_add_f32 v[70:71], v[70:71], v[144:145]
	v_pk_add_f32 v[72:73], v[72:73], v[146:147]
	v_lshlrev_b32_e32 v144, 16, v246
	v_and_b32_e32 v145, 0xffff0000, v246
	v_lshlrev_b32_e32 v146, 16, v247
	v_and_b32_e32 v147, 0xffff0000, v247
	v_pk_add_f32 v[66:67], v[66:67], v[144:145]
	v_pk_add_f32 v[68:69], v[68:69], v[146:147]
	v_mul_f32_e32 v248, v70, v70
	v_mul_f32_e32 v249, v66, v66
	v_fmac_f32_e32 v248, v71, v71
	v_fmac_f32_e32 v249, v67, v67
	v_fmac_f32_e32 v248, v72, v72
	v_fmac_f32_e32 v249, v68, v68
	v_fmac_f32_e32 v248, v73, v73
	v_fmac_f32_e32 v249, v69, v69
	v_add_f32_e32 v248, v248, v249
	v_add_f32_e32 v252, v252, v248
	v_cvt_pk_bf16_f32 v244, v70, v71
	v_cvt_pk_bf16_f32 v245, v72, v73
	v_cvt_pk_bf16_f32 v246, v66, v67
	v_cvt_pk_bf16_f32 v247, v68, v69
	s_nop 1
	v_permlane16_swap_b32_e32 v244, v246
	v_permlane16_swap_b32_e32 v245, v247
	global_store_dwordx4 v253, v[244:247], s[16:17] offset:256
	ds_bpermute_b32 v248, v118, v252
	s_waitcnt lgkmcnt(0)
	v_add_f32_e32 v252, v252, v248
	ds_bpermute_b32 v248, v116, v252
	s_nop 0
	global_load_dwordx4 v[244:247], v251, s[8:9] offset:256
	s_and_saveexec_b64 s[46:47], vcc
	s_cbranch_execz .Lepi14_g3
	s_waitcnt lgkmcnt(0)
	v_add_f32_e32 v252, v252, v248
	global_store_dword v[148:149], v252, off offset:3072
.Lepi14_g3:
	s_or_b64 exec, exec, s[46:47]
	s_waitcnt lgkmcnt(0)
	s_waitcnt vmcnt(18)
	v_permlane16_swap_b32_e32 v216, v218
	v_permlane16_swap_b32_e32 v217, v219
	v_lshlrev_b32_e32 v144, 16, v216
	v_and_b32_e32 v145, 0xffff0000, v216
	v_lshlrev_b32_e32 v146, 16, v217
	v_and_b32_e32 v147, 0xffff0000, v217
	v_pk_add_f32 v[62:63], v[62:63], v[144:145]
	v_pk_add_f32 v[64:65], v[64:65], v[146:147]
	v_lshlrev_b32_e32 v144, 16, v218
	v_and_b32_e32 v145, 0xffff0000, v218
	v_lshlrev_b32_e32 v146, 16, v219
	v_and_b32_e32 v147, 0xffff0000, v219
	v_pk_add_f32 v[58:59], v[58:59], v[144:145]
	v_pk_add_f32 v[60:61], v[60:61], v[146:147]
	v_mul_f32_e32 v248, v62, v62
	v_mul_f32_e32 v249, v58, v58
	v_fmac_f32_e32 v248, v63, v63
	v_fmac_f32_e32 v249, v59, v59
	v_fmac_f32_e32 v248, v64, v64
	v_fmac_f32_e32 v249, v60, v60
	v_fmac_f32_e32 v248, v65, v65
	v_fmac_f32_e32 v249, v61, v61
	v_add_f32_e32 v248, v248, v249
	v_mov_b32_e32 v252, v248
	v_cvt_pk_bf16_f32 v216, v62, v63
	v_cvt_pk_bf16_f32 v217, v64, v65
	v_cvt_pk_bf16_f32 v218, v58, v59
	v_cvt_pk_bf16_f32 v219, v60, v61
	s_nop 1
	v_permlane16_swap_b32_e32 v216, v218
	v_permlane16_swap_b32_e32 v217, v219
	v_add_u32_e32 v253, 0x40000, v250
	global_store_dwordx4 v253, v[216:219], s[16:17]
	s_waitcnt vmcnt(17)
	v_permlane16_swap_b32_e32 v220, v222
	v_permlane16_swap_b32_e32 v221, v223
	v_lshlrev_b32_e32 v144, 16, v220
	v_and_b32_e32 v145, 0xffff0000, v220
	v_lshlrev_b32_e32 v146, 16, v221
	v_and_b32_e32 v147, 0xffff0000, v221
	v_pk_add_f32 v[54:55], v[54:55], v[144:145]
	v_pk_add_f32 v[56:57], v[56:57], v[146:147]
	v_lshlrev_b32_e32 v144, 16, v222
	v_and_b32_e32 v145, 0xffff0000, v222
	v_lshlrev_b32_e32 v146, 16, v223
	v_and_b32_e32 v147, 0xffff0000, v223
	v_pk_add_f32 v[50:51], v[50:51], v[144:145]
	v_pk_add_f32 v[52:53], v[52:53], v[146:147]
	v_mul_f32_e32 v248, v54, v54
	v_mul_f32_e32 v249, v50, v50
	v_fmac_f32_e32 v248, v55, v55
	v_fmac_f32_e32 v249, v51, v51
	v_fmac_f32_e32 v248, v56, v56
	v_fmac_f32_e32 v249, v52, v52
	v_fmac_f32_e32 v248, v57, v57
	v_fmac_f32_e32 v249, v53, v53
	v_add_f32_e32 v248, v248, v249
	v_add_f32_e32 v252, v252, v248
	v_cvt_pk_bf16_f32 v220, v54, v55
	v_cvt_pk_bf16_f32 v221, v56, v57
	v_cvt_pk_bf16_f32 v222, v50, v51
	v_cvt_pk_bf16_f32 v223, v52, v53
	s_nop 1
	v_permlane16_swap_b32_e32 v220, v222
	v_permlane16_swap_b32_e32 v221, v223
	global_store_dwordx4 v253, v[220:223], s[16:17] offset:256
	ds_bpermute_b32 v248, v118, v252
	s_waitcnt lgkmcnt(0)
	v_add_f32_e32 v252, v252, v248
	ds_bpermute_b32 v248, v116, v252
	s_and_saveexec_b64 s[46:47], vcc
	s_cbranch_execz .Lepi14_g4
	s_waitcnt lgkmcnt(0)
	v_add_f32_e32 v252, v252, v248
	global_store_dword v[150:151], v252, off
.Lepi14_g4:
	s_or_b64 exec, exec, s[46:47]
	s_waitcnt lgkmcnt(0)
	s_waitcnt vmcnt(16)
	v_permlane16_swap_b32_e32 v224, v226
	v_permlane16_swap_b32_e32 v225, v227
	v_lshlrev_b32_e32 v144, 16, v224
	v_and_b32_e32 v145, 0xffff0000, v224
	v_lshlrev_b32_e32 v146, 16, v225
	v_and_b32_e32 v147, 0xffff0000, v225
	v_pk_add_f32 v[46:47], v[46:47], v[144:145]
	v_pk_add_f32 v[48:49], v[48:49], v[146:147]
	v_lshlrev_b32_e32 v144, 16, v226
	v_and_b32_e32 v145, 0xffff0000, v226
	v_lshlrev_b32_e32 v146, 16, v227
	v_and_b32_e32 v147, 0xffff0000, v227
	v_pk_add_f32 v[42:43], v[42:43], v[144:145]
	v_pk_add_f32 v[44:45], v[44:45], v[146:147]
	v_mul_f32_e32 v248, v46, v46
	v_mul_f32_e32 v249, v42, v42
	v_fmac_f32_e32 v248, v47, v47
	v_fmac_f32_e32 v249, v43, v43
	v_fmac_f32_e32 v248, v48, v48
	v_fmac_f32_e32 v249, v44, v44
	v_fmac_f32_e32 v248, v49, v49
	v_fmac_f32_e32 v249, v45, v45
	v_add_f32_e32 v248, v248, v249
	v_mov_b32_e32 v252, v248
	v_cvt_pk_bf16_f32 v224, v46, v47
	v_cvt_pk_bf16_f32 v225, v48, v49
	v_cvt_pk_bf16_f32 v226, v42, v43
	v_cvt_pk_bf16_f32 v227, v44, v45
	s_nop 1
	v_permlane16_swap_b32_e32 v224, v226
	v_permlane16_swap_b32_e32 v225, v227
	v_add_u32_e32 v253, 0x48000, v250
	global_store_dwordx4 v253, v[224:227], s[16:17]
	s_waitcnt vmcnt(15)
	v_permlane16_swap_b32_e32 v228, v230
	v_permlane16_swap_b32_e32 v229, v231
	v_lshlrev_b32_e32 v144, 16, v228
	v_and_b32_e32 v145, 0xffff0000, v228
	v_lshlrev_b32_e32 v146, 16, v229
	v_and_b32_e32 v147, 0xffff0000, v229
	v_pk_add_f32 v[38:39], v[38:39], v[144:145]
	v_pk_add_f32 v[40:41], v[40:41], v[146:147]
	v_lshlrev_b32_e32 v144, 16, v230
	v_and_b32_e32 v145, 0xffff0000, v230
	v_lshlrev_b32_e32 v146, 16, v231
	v_and_b32_e32 v147, 0xffff0000, v231
	v_pk_add_f32 v[34:35], v[34:35], v[144:145]
	v_pk_add_f32 v[36:37], v[36:37], v[146:147]
	v_mul_f32_e32 v248, v38, v38
	v_mul_f32_e32 v249, v34, v34
	v_fmac_f32_e32 v248, v39, v39
	v_fmac_f32_e32 v249, v35, v35
	v_fmac_f32_e32 v248, v40, v40
	v_fmac_f32_e32 v249, v36, v36
	v_fmac_f32_e32 v248, v41, v41
	v_fmac_f32_e32 v249, v37, v37
	v_add_f32_e32 v248, v248, v249
	v_add_f32_e32 v252, v252, v248
	v_cvt_pk_bf16_f32 v228, v38, v39
	v_cvt_pk_bf16_f32 v229, v40, v41
	v_cvt_pk_bf16_f32 v230, v34, v35
	v_cvt_pk_bf16_f32 v231, v36, v37
	s_nop 1
	v_permlane16_swap_b32_e32 v228, v230
	v_permlane16_swap_b32_e32 v229, v231
	global_store_dwordx4 v253, v[228:231], s[16:17] offset:256
	ds_bpermute_b32 v248, v118, v252
	s_waitcnt lgkmcnt(0)
	v_add_f32_e32 v252, v252, v248
	ds_bpermute_b32 v248, v116, v252
	s_and_saveexec_b64 s[46:47], vcc
	s_cbranch_execz .Lepi14_g5
	s_waitcnt lgkmcnt(0)
	v_add_f32_e32 v252, v252, v248
	global_store_dword v[150:151], v252, off offset:1024
.Lepi14_g5:
	s_or_b64 exec, exec, s[46:47]
	s_waitcnt lgkmcnt(0)
	s_waitcnt vmcnt(14)
	v_permlane16_swap_b32_e32 v232, v234
	v_permlane16_swap_b32_e32 v233, v235
	v_lshlrev_b32_e32 v144, 16, v232
	v_and_b32_e32 v145, 0xffff0000, v232
	v_lshlrev_b32_e32 v146, 16, v233
	v_and_b32_e32 v147, 0xffff0000, v233
	v_pk_add_f32 v[30:31], v[30:31], v[144:145]
	v_pk_add_f32 v[32:33], v[32:33], v[146:147]
	v_lshlrev_b32_e32 v144, 16, v234
	v_and_b32_e32 v145, 0xffff0000, v234
	v_lshlrev_b32_e32 v146, 16, v235
	v_and_b32_e32 v147, 0xffff0000, v235
	v_pk_add_f32 v[26:27], v[26:27], v[144:145]
	v_pk_add_f32 v[28:29], v[28:29], v[146:147]
	v_mul_f32_e32 v248, v30, v30
	v_mul_f32_e32 v249, v26, v26
	v_fmac_f32_e32 v248, v31, v31
	v_fmac_f32_e32 v249, v27, v27
	v_fmac_f32_e32 v248, v32, v32
	v_fmac_f32_e32 v249, v28, v28
	v_fmac_f32_e32 v248, v33, v33
	v_fmac_f32_e32 v249, v29, v29
	v_add_f32_e32 v248, v248, v249
	v_mov_b32_e32 v252, v248
	v_cvt_pk_bf16_f32 v232, v30, v31
	v_cvt_pk_bf16_f32 v233, v32, v33
	v_cvt_pk_bf16_f32 v234, v26, v27
	v_cvt_pk_bf16_f32 v235, v28, v29
	s_nop 1
	v_permlane16_swap_b32_e32 v232, v234
	v_permlane16_swap_b32_e32 v233, v235
	v_add_u32_e32 v253, 0x50000, v250
	global_store_dwordx4 v253, v[232:235], s[16:17]
	s_waitcnt vmcnt(13)
	v_permlane16_swap_b32_e32 v236, v238
	v_permlane16_swap_b32_e32 v237, v239
	v_lshlrev_b32_e32 v144, 16, v236
	v_and_b32_e32 v145, 0xffff0000, v236
	v_lshlrev_b32_e32 v146, 16, v237
	v_and_b32_e32 v147, 0xffff0000, v237
	v_pk_add_f32 v[22:23], v[22:23], v[144:145]
	v_pk_add_f32 v[24:25], v[24:25], v[146:147]
	v_lshlrev_b32_e32 v144, 16, v238
	v_and_b32_e32 v145, 0xffff0000, v238
	v_lshlrev_b32_e32 v146, 16, v239
	v_and_b32_e32 v147, 0xffff0000, v239
	v_pk_add_f32 v[18:19], v[18:19], v[144:145]
	v_pk_add_f32 v[20:21], v[20:21], v[146:147]
	v_mul_f32_e32 v248, v22, v22
	v_mul_f32_e32 v249, v18, v18
	v_fmac_f32_e32 v248, v23, v23
	v_fmac_f32_e32 v249, v19, v19
	v_fmac_f32_e32 v248, v24, v24
	v_fmac_f32_e32 v249, v20, v20
	v_fmac_f32_e32 v248, v25, v25
	v_fmac_f32_e32 v249, v21, v21
	v_add_f32_e32 v248, v248, v249
	v_add_f32_e32 v252, v252, v248
	v_cvt_pk_bf16_f32 v236, v22, v23
	v_cvt_pk_bf16_f32 v237, v24, v25
	v_cvt_pk_bf16_f32 v238, v18, v19
	v_cvt_pk_bf16_f32 v239, v20, v21
	s_nop 1
	v_permlane16_swap_b32_e32 v236, v238
	v_permlane16_swap_b32_e32 v237, v239
	global_store_dwordx4 v253, v[236:239], s[16:17] offset:256
	ds_bpermute_b32 v248, v118, v252
	s_waitcnt lgkmcnt(0)
	v_add_f32_e32 v252, v252, v248
	ds_bpermute_b32 v248, v116, v252
	s_and_saveexec_b64 s[46:47], vcc
	s_cbranch_execz .Lepi14_g6
	s_waitcnt lgkmcnt(0)
	v_add_f32_e32 v252, v252, v248
	global_store_dword v[150:151], v252, off offset:2048
.Lepi14_g6:
	s_or_b64 exec, exec, s[46:47]
	s_waitcnt lgkmcnt(0)
	s_waitcnt vmcnt(12)
	v_permlane16_swap_b32_e32 v240, v242
	v_permlane16_swap_b32_e32 v241, v243
	v_lshlrev_b32_e32 v144, 16, v240
	v_and_b32_e32 v145, 0xffff0000, v240
	v_lshlrev_b32_e32 v146, 16, v241
	v_and_b32_e32 v147, 0xffff0000, v241
	v_pk_add_f32 v[14:15], v[14:15], v[144:145]
	v_pk_add_f32 v[16:17], v[16:17], v[146:147]
	v_lshlrev_b32_e32 v144, 16, v242
	v_and_b32_e32 v145, 0xffff0000, v242
	v_lshlrev_b32_e32 v146, 16, v243
	v_and_b32_e32 v147, 0xffff0000, v243
	v_pk_add_f32 v[10:11], v[10:11], v[144:145]
	v_pk_add_f32 v[12:13], v[12:13], v[146:147]
	v_mul_f32_e32 v248, v14, v14
	v_mul_f32_e32 v249, v10, v10
	v_fmac_f32_e32 v248, v15, v15
	v_fmac_f32_e32 v249, v11, v11
	v_fmac_f32_e32 v248, v16, v16
	v_fmac_f32_e32 v249, v12, v12
	v_fmac_f32_e32 v248, v17, v17
	v_fmac_f32_e32 v249, v13, v13
	v_add_f32_e32 v248, v248, v249
	v_mov_b32_e32 v252, v248
	v_cvt_pk_bf16_f32 v240, v14, v15
	v_cvt_pk_bf16_f32 v241, v16, v17
	v_cvt_pk_bf16_f32 v242, v10, v11
	v_cvt_pk_bf16_f32 v243, v12, v13
	s_nop 1
	v_permlane16_swap_b32_e32 v240, v242
	v_permlane16_swap_b32_e32 v241, v243
	v_add_u32_e32 v253, 0x58000, v250
	global_store_dwordx4 v253, v[240:243], s[16:17]
	s_waitcnt vmcnt(11)
	v_permlane16_swap_b32_e32 v244, v246
	v_permlane16_swap_b32_e32 v245, v247
	v_lshlrev_b32_e32 v144, 16, v244
	v_and_b32_e32 v145, 0xffff0000, v244
	v_lshlrev_b32_e32 v146, 16, v245
	v_and_b32_e32 v147, 0xffff0000, v245
	v_pk_add_f32 v[6:7], v[6:7], v[144:145]
	v_pk_add_f32 v[8:9], v[8:9], v[146:147]
	v_lshlrev_b32_e32 v144, 16, v246
	v_and_b32_e32 v145, 0xffff0000, v246
	v_lshlrev_b32_e32 v146, 16, v247
	v_and_b32_e32 v147, 0xffff0000, v247
	v_pk_add_f32 v[2:3], v[2:3], v[144:145]
	v_pk_add_f32 v[4:5], v[4:5], v[146:147]
	v_mul_f32_e32 v248, v6, v6
	v_mul_f32_e32 v249, v2, v2
	v_fmac_f32_e32 v248, v7, v7
	v_fmac_f32_e32 v249, v3, v3
	v_fmac_f32_e32 v248, v8, v8
	v_fmac_f32_e32 v249, v4, v4
	v_fmac_f32_e32 v248, v9, v9
	v_fmac_f32_e32 v249, v5, v5
	v_add_f32_e32 v248, v248, v249
	v_add_f32_e32 v252, v252, v248
	v_cvt_pk_bf16_f32 v244, v6, v7
	v_cvt_pk_bf16_f32 v245, v8, v9
	v_cvt_pk_bf16_f32 v246, v2, v3
	v_cvt_pk_bf16_f32 v247, v4, v5
	s_nop 1
	v_permlane16_swap_b32_e32 v244, v246
	v_permlane16_swap_b32_e32 v245, v247
	global_store_dwordx4 v253, v[244:247], s[16:17] offset:256
	ds_bpermute_b32 v248, v118, v252
	s_waitcnt lgkmcnt(0)
	v_add_f32_e32 v252, v252, v248
	ds_bpermute_b32 v248, v116, v252
	s_and_saveexec_b64 s[46:47], vcc
	s_cbranch_execz .LBB0_2559
	s_waitcnt lgkmcnt(0)
	v_add_f32_e32 v252, v252, v248
	global_store_dword v[150:151], v252, off offset:3072
